# GEMM K-loop variant: only 6 fragment reads before the first MFMAs, rest streamed in the first group
# baseline (speedup 1.0000x reference)
.LBB0_212:
	s_add_i32 s1, s0, 0x10000
	s_and_b32 s11, s1, 0x10000
	s_waitcnt vmcnt(0)
	s_barrier
	s_and_b32 s0, s0, 0x10000
	s_add_i32 s0, s0, 0
	v_add_u32_e32 v164, s0, v154
	v_add_u32_e32 v165, v164, v151
	ds_read_b128 v[186:189], v165 offset:32768
	ds_read_b128 v[192:195], v165 offset:34816
	ds_read_b128 v[198:201], v165 offset:36864
	ds_read_b128 v[204:207], v165 offset:38912
	v_add_u32_e32 v248, v164, v150
	v_add_u32_e32 v155, s0, v153
	v_add_u32_e32 v249, v155, v150
	v_add_u32_e32 v155, v155, v151
	ds_read_b128 v[156:159], v155
	ds_read_b128 v[160:163], v155 offset:2048
	v_add_u32_e32 v251, s11, v152
	v_add_u32_e32 v240, 0x2000, v251
	v_readfirstlane_b32 s11, v251
	v_lshl_add_u64 v[174:175], v[144:145], 0, s[8:9]
	s_mov_b32 m0, s11
	v_readfirstlane_b32 s11, v240
	v_add_u32_e32 v240, 0x4000, v251
	global_load_lds_dwordx4 v[174:175], off
	v_lshl_add_u64 v[174:175], v[134:135], 0, s[8:9]
	s_mov_b32 m0, s11
	s_waitcnt lgkmcnt(1)
	v_mfma_f32_16x16x32_bf16 v[124:127], v[156:159], v[186:189], v[124:127]
	ds_read_b128 v[178:181], v155 offset:4096
	v_mfma_f32_16x16x32_bf16 v[120:123], v[156:159], v[192:195], v[120:123]
	ds_read_b128 v[182:185], v155 offset:6144
	v_readfirstlane_b32 s11, v240
	v_add_u32_e32 v240, 0x6000, v251
	v_mfma_f32_16x16x32_bf16 v[116:119], v[156:159], v[198:201], v[116:119]
	ds_read_b128 v[224:227], v165 offset:40960
	global_load_lds_dwordx4 v[174:175], off
	v_lshl_add_u64 v[174:175], v[132:133], 0, s[8:9]
	v_mfma_f32_16x16x32_bf16 v[112:115], v[156:159], v[204:207], v[112:115]
	ds_read_b128 v[228:231], v165 offset:43008
	s_mov_b32 m0, s11
	v_readfirstlane_b32 s11, v240
	s_waitcnt lgkmcnt(4)
	v_mfma_f32_16x16x32_bf16 v[104:107], v[160:163], v[186:189], v[104:107]
	ds_read_b128 v[232:235], v165 offset:45056
	global_load_lds_dwordx4 v[174:175], off
	v_lshl_add_u64 v[174:175], v[130:131], 0, s[8:9]
	v_mfma_f32_16x16x32_bf16 v[96:99], v[160:163], v[192:195], v[96:99]
	ds_read_b128 v[236:239], v165 offset:47104
	s_mov_b32 m0, s11
	v_add_u32_e32 v250, 0x8000, v251
	v_mfma_f32_16x16x32_bf16 v[88:91], v[160:163], v[198:201], v[88:91]
	ds_read_b128 v[208:211], v249
	global_load_lds_dwordx4 v[174:175], off
	v_lshl_add_u64 v[174:175], v[128:129], 0, s[8:9]
	v_mfma_f32_16x16x32_bf16 v[80:83], v[160:163], v[204:207], v[80:83]
	ds_read_b128 v[212:215], v249 offset:2048
	v_readfirstlane_b32 s11, v250
	v_add_u32_e32 v250, 0xa000, v251
	s_waitcnt lgkmcnt(7)
	v_mfma_f32_16x16x32_bf16 v[72:75], v[178:181], v[186:189], v[72:75]
	ds_read_b128 v[216:219], v249 offset:4096
	v_lshl_add_u64 v[240:241], v[174:175], 0, s[66:67]
	s_mov_b32 m0, s11
	v_mfma_f32_16x16x32_bf16 v[64:67], v[178:181], v[192:195], v[64:67]
	ds_read_b128 v[220:223], v249 offset:6144
	s_mov_b64 s[12:13], 0x22080
	v_readfirstlane_b32 s11, v250
	v_mfma_f32_16x16x32_bf16 v[56:59], v[178:181], v[198:201], v[56:59]
	v_add_u32_e32 v250, 0xc000, v251
	global_load_lds_dwordx4 v[240:241], off
	v_mfma_f32_16x16x32_bf16 v[48:51], v[178:181], v[204:207], v[48:51]
	v_lshl_add_u64 v[240:241], v[174:175], 0, s[12:13]
	s_mov_b32 m0, s11
	s_waitcnt lgkmcnt(8)
	v_mfma_f32_16x16x32_bf16 v[40:43], v[182:185], v[186:189], v[40:43]
	s_mov_b64 s[12:13], 0x44080
	v_readfirstlane_b32 s11, v250
	v_mfma_f32_16x16x32_bf16 v[32:35], v[182:185], v[192:195], v[32:35]
	v_add_u32_e32 v251, 0xe000, v251
	global_load_lds_dwordx4 v[240:241], off
	v_mfma_f32_16x16x32_bf16 v[24:27], v[182:185], v[198:201], v[24:27]
	v_lshl_add_u64 v[240:241], v[174:175], 0, s[12:13]
	s_mov_b32 m0, s11
	v_mfma_f32_16x16x32_bf16 v[16:19], v[182:185], v[204:207], v[16:19]
	s_mov_b64 s[12:13], 0x66080
	v_readfirstlane_b32 s11, v251
	s_waitcnt lgkmcnt(4)
	v_mfma_f32_16x16x32_bf16 v[100:103], v[156:159], v[224:227], v[100:103]
	global_load_lds_dwordx4 v[240:241], off
	v_lshl_add_u64 v[174:175], v[174:175], 0, s[12:13]
	v_mfma_f32_16x16x32_bf16 v[92:95], v[156:159], v[228:231], v[92:95]
	s_mov_b32 m0, s11
	global_load_lds_dwordx4 v[174:175], off
	v_mfma_f32_16x16x32_bf16 v[84:87], v[156:159], v[232:235], v[84:87]
	ds_read_b128 v[186:189], v248 offset:32768
	v_mfma_f32_16x16x32_bf16 v[76:79], v[156:159], v[236:239], v[76:79]
	ds_read_b128 v[192:195], v248 offset:34816
	v_mfma_f32_16x16x32_bf16 v[68:71], v[160:163], v[224:227], v[68:71]
	ds_read_b128 v[198:201], v248 offset:36864
	v_mfma_f32_16x16x32_bf16 v[60:63], v[160:163], v[228:231], v[60:63]
	ds_read_b128 v[204:207], v248 offset:38912
	v_mfma_f32_16x16x32_bf16 v[52:55], v[160:163], v[232:235], v[52:55]
	v_mfma_f32_16x16x32_bf16 v[44:47], v[160:163], v[236:239], v[44:47]
	v_mfma_f32_16x16x32_bf16 v[36:39], v[178:181], v[224:227], v[36:39]
	v_mfma_f32_16x16x32_bf16 v[28:31], v[178:181], v[228:231], v[28:31]
	v_mfma_f32_16x16x32_bf16 v[20:23], v[178:181], v[232:235], v[20:23]
	v_mfma_f32_16x16x32_bf16 v[12:15], v[178:181], v[236:239], v[12:15]
	v_mfma_f32_16x16x32_bf16 v[8:11], v[182:185], v[224:227], v[8:11]
	v_mfma_f32_16x16x32_bf16 v[4:7], v[182:185], v[228:231], v[4:7]
	v_mfma_f32_16x16x32_bf16 v[0:3], v[182:185], v[232:235], v[0:3]
	v_mfma_f32_16x16x32_bf16 v[108:111], v[182:185], v[236:239], v[108:111]
	s_waitcnt lgkmcnt(0)
	v_mfma_f32_16x16x32_bf16 v[124:127], v[208:211], v[186:189], v[124:127]
	ds_read_b128 v[224:227], v248 offset:40960
	v_mfma_f32_16x16x32_bf16 v[120:123], v[208:211], v[192:195], v[120:123]
	ds_read_b128 v[228:231], v248 offset:43008
	v_mfma_f32_16x16x32_bf16 v[116:119], v[208:211], v[198:201], v[116:119]
	ds_read_b128 v[232:235], v248 offset:45056
	v_mfma_f32_16x16x32_bf16 v[112:115], v[208:211], v[204:207], v[112:115]
	ds_read_b128 v[236:239], v248 offset:47104
	v_mfma_f32_16x16x32_bf16 v[104:107], v[212:215], v[186:189], v[104:107]
	v_mfma_f32_16x16x32_bf16 v[96:99], v[212:215], v[192:195], v[96:99]
	v_mfma_f32_16x16x32_bf16 v[88:91], v[212:215], v[198:201], v[88:91]
	v_mfma_f32_16x16x32_bf16 v[80:83], v[212:215], v[204:207], v[80:83]
	v_mfma_f32_16x16x32_bf16 v[72:75], v[216:219], v[186:189], v[72:75]
	v_mfma_f32_16x16x32_bf16 v[64:67], v[216:219], v[192:195], v[64:67]
	v_mfma_f32_16x16x32_bf16 v[56:59], v[216:219], v[198:201], v[56:59]
	v_mfma_f32_16x16x32_bf16 v[48:51], v[216:219], v[204:207], v[48:51]
	v_mfma_f32_16x16x32_bf16 v[40:43], v[220:223], v[186:189], v[40:43]
	v_mfma_f32_16x16x32_bf16 v[32:35], v[220:223], v[192:195], v[32:35]
	v_mfma_f32_16x16x32_bf16 v[24:27], v[220:223], v[198:201], v[24:27]
	v_mfma_f32_16x16x32_bf16 v[16:19], v[220:223], v[204:207], v[16:19]
	s_waitcnt lgkmcnt(0)
	v_mfma_f32_16x16x32_bf16 v[100:103], v[208:211], v[224:227], v[100:103]
	v_mfma_f32_16x16x32_bf16 v[92:95], v[208:211], v[228:231], v[92:95]
	v_mfma_f32_16x16x32_bf16 v[84:87], v[208:211], v[232:235], v[84:87]
	v_mfma_f32_16x16x32_bf16 v[76:79], v[208:211], v[236:239], v[76:79]
	v_mfma_f32_16x16x32_bf16 v[68:71], v[212:215], v[224:227], v[68:71]
	v_mfma_f32_16x16x32_bf16 v[60:63], v[212:215], v[228:231], v[60:63]
	v_mfma_f32_16x16x32_bf16 v[52:55], v[212:215], v[232:235], v[52:55]
	v_mfma_f32_16x16x32_bf16 v[44:47], v[212:215], v[236:239], v[44:47]
	v_mfma_f32_16x16x32_bf16 v[36:39], v[216:219], v[224:227], v[36:39]
	v_mfma_f32_16x16x32_bf16 v[28:31], v[216:219], v[228:231], v[28:31]
	v_mfma_f32_16x16x32_bf16 v[20:23], v[216:219], v[232:235], v[20:23]
	v_mfma_f32_16x16x32_bf16 v[12:15], v[216:219], v[236:239], v[12:15]
	s_add_u32 s8, s8, 0x80
	s_addc_u32 s9, s9, 0
	s_cmpk_eq_i32 s8, 0x780
	s_mov_b32 s0, s1
	v_mfma_f32_16x16x32_bf16 v[8:11], v[220:223], v[224:227], v[8:11]
	v_mfma_f32_16x16x32_bf16 v[4:7], v[220:223], v[228:231], v[4:7]
	v_mfma_f32_16x16x32_bf16 v[0:3], v[220:223], v[232:235], v[0:3]
	v_mfma_f32_16x16x32_bf16 v[108:111], v[220:223], v[236:239], v[108:111]
	s_cbranch_scc0 .LBB0_212
	s_add_i32 s0, 0, 0x10000
	v_add_u32_e32 v144, s0, v154
	v_add_u32_e32 v162, s0, v153
	v_add_u32_e32 v145, v144, v151
	v_add_u32_e32 v151, v162, v151
	s_waitcnt vmcnt(0)
	s_barrier
	ds_read_b128 v[128:131], v145 offset:38912
	ds_read_b128 v[132:135], v145 offset:36864
	ds_read_b128 v[154:157], v145 offset:34816
	ds_read_b128 v[158:161], v145 offset:32768
	ds_read_b128 v[178:181], v151 offset:6144
	ds_read_b128 v[182:185], v151 offset:4096
	ds_read_b128 v[186:189], v151 offset:2048
	ds_read_b128 v[204:207], v151
	s_waitcnt lgkmcnt(0)
	v_mfma_f32_16x16x32_bf16 v[124:127], v[204:207], v[158:161], v[124:127]
	v_mfma_f32_16x16x32_bf16 v[120:123], v[204:207], v[154:157], v[120:123]
	v_mfma_f32_16x16x32_bf16 v[116:119], v[204:207], v[132:135], v[116:119]
	v_mfma_f32_16x16x32_bf16 v[112:115], v[204:207], v[128:131], v[112:115]
	v_mfma_f32_16x16x32_bf16 v[104:107], v[186:189], v[158:161], v[104:107]
	v_mfma_f32_16x16x32_bf16 v[72:75], v[182:185], v[158:161], v[72:75]
	v_mfma_f32_16x16x32_bf16 v[64:67], v[182:185], v[154:157], v[64:67]
	v_mfma_f32_16x16x32_bf16 v[56:59], v[182:185], v[132:135], v[56:59]
	v_mfma_f32_16x16x32_bf16 v[48:51], v[182:185], v[128:131], v[48:51]
	v_mfma_f32_16x16x32_bf16 v[208:211], v[186:189], v[154:157], v[96:99]
	v_mfma_f32_16x16x32_bf16 v[212:215], v[186:189], v[132:135], v[88:91]
	v_mfma_f32_16x16x32_bf16 v[216:219], v[186:189], v[128:131], v[80:83]
	v_mfma_f32_16x16x32_bf16 v[158:161], v[178:181], v[158:161], v[40:43]
	v_mfma_f32_16x16x32_bf16 v[152:155], v[178:181], v[154:157], v[32:35]
	v_mfma_f32_16x16x32_bf16 v[132:135], v[178:181], v[132:135], v[24:27]
	v_mfma_f32_16x16x32_bf16 v[128:131], v[178:181], v[128:131], v[16:19]
	s_nop 2
	ds_read_b128 v[16:19], v145 offset:40960
	ds_read_b128 v[24:27], v145 offset:43008
	ds_read_b128 v[32:35], v145 offset:45056
	ds_read_b128 v[40:43], v145 offset:47104
	s_waitcnt lgkmcnt(0)
	v_mfma_f32_16x16x32_bf16 v[100:103], v[204:207], v[16:19], v[100:103]
	v_mfma_f32_16x16x32_bf16 v[92:95], v[204:207], v[24:27], v[92:95]
	v_mfma_f32_16x16x32_bf16 v[220:223], v[204:207], v[32:35], v[84:87]
	v_mfma_f32_16x16x32_bf16 v[76:79], v[204:207], v[40:43], v[76:79]
	v_mfma_f32_16x16x32_bf16 v[68:71], v[186:189], v[16:19], v[68:71]
	v_mfma_f32_16x16x32_bf16 v[60:63], v[186:189], v[24:27], v[60:63]
	v_mfma_f32_16x16x32_bf16 v[204:207], v[186:189], v[32:35], v[52:55]
	v_mfma_f32_16x16x32_bf16 v[44:47], v[186:189], v[40:43], v[44:47]
	v_mfma_f32_16x16x32_bf16 v[186:189], v[182:185], v[16:19], v[36:39]
	v_mfma_f32_16x16x32_bf16 v[224:227], v[182:185], v[24:27], v[28:31]
	v_mfma_f32_16x16x32_bf16 v[228:231], v[182:185], v[32:35], v[20:23]
	v_mfma_f32_16x16x32_bf16 v[182:185], v[182:185], v[40:43], v[12:15]
	v_mfma_f32_16x16x32_bf16 v[232:235], v[178:181], v[16:19], v[8:11]
	v_mfma_f32_16x16x32_bf16 v[236:239], v[178:181], v[24:27], v[4:7]
	v_mfma_f32_16x16x32_bf16 v[240:243], v[178:181], v[32:35], v[0:3]
	v_mfma_f32_16x16x32_bf16 v[244:247], v[178:181], v[40:43], v[108:111]
	s_nop 1
	v_add_u32_e32 v0, v162, v150
	v_add_u32_e32 v144, v144, v150
	ds_read_b128 v[108:111], v0
	ds_read_b128 v[178:181], v0 offset:2048
	ds_read_b128 v[248:251], v0 offset:4096
	ds_read_b128 v[192:195], v0 offset:6144
	ds_read_b128 v[0:3], v144 offset:32768
	ds_read_b128 v[4:7], v144 offset:34816
	ds_read_b128 v[198:201], v144 offset:36864
	ds_read_b128 v[162:165], v144 offset:38912
	s_waitcnt lgkmcnt(0)
	v_mfma_f32_16x16x32_bf16 v[88:91], v[108:111], v[0:3], v[124:127]
	v_mfma_f32_16x16x32_bf16 v[96:99], v[108:111], v[4:7], v[120:123]
	v_mfma_f32_16x16x32_bf16 v[80:83], v[108:111], v[198:201], v[116:119]
	v_mfma_f32_16x16x32_bf16 v[84:87], v[108:111], v[162:165], v[112:115]
	v_mfma_f32_16x16x32_bf16 v[40:43], v[178:181], v[0:3], v[104:107]
	v_mfma_f32_16x16x32_bf16 v[52:55], v[178:181], v[4:7], v[208:211]
	v_mfma_f32_16x16x32_bf16 v[32:35], v[178:181], v[198:201], v[212:215]
	v_mfma_f32_16x16x32_bf16 v[36:39], v[178:181], v[162:165], v[216:219]
	v_mfma_f32_16x16x32_bf16 v[24:27], v[248:251], v[0:3], v[72:75]
	v_mfma_f32_16x16x32_bf16 v[28:31], v[248:251], v[4:7], v[64:67]
	v_mfma_f32_16x16x32_bf16 v[16:19], v[248:251], v[198:201], v[56:59]
	v_mfma_f32_16x16x32_bf16 v[20:23], v[248:251], v[162:165], v[48:51]
	v_mfma_f32_16x16x32_bf16 v[8:11], v[192:195], v[0:3], v[158:161]
	v_mfma_f32_16x16x32_bf16 v[12:15], v[192:195], v[4:7], v[152:155]
	v_mfma_f32_16x16x32_bf16 v[0:3], v[192:195], v[198:201], v[132:135]
	v_mfma_f32_16x16x32_bf16 v[4:7], v[192:195], v[162:165], v[128:131]
	ds_read_b128 v[48:51], v144 offset:40960
	ds_read_b128 v[64:67], v144 offset:43008
	s_nop 0
	ds_read_b128 v[128:131], v144 offset:45056
	ds_read_b128 v[132:135], v144 offset:47104
	s_waitcnt lgkmcnt(0)
	v_mfma_f32_16x16x32_bf16 v[104:107], v[178:181], v[48:51], v[68:71]
	v_cmp_ne_u32_e64 s[8:9], 0, v146
	v_cmp_eq_u32_e32 vcc, 0, v146
	s_waitcnt vmcnt(0)
	v_lshl_or_b32 v68, v148, 2, v149
	v_lshl_add_u32 v69, v147, 2, 0
	v_mfma_f32_16x16x32_bf16 v[120:123], v[108:111], v[48:51], v[100:103]
	s_barrier
	v_mfma_f32_16x16x32_bf16 v[124:127], v[108:111], v[64:67], v[92:95]
	v_mfma_f32_16x16x32_bf16 v[112:115], v[108:111], v[128:131], v[220:223]
	v_mfma_f32_16x16x32_bf16 v[116:119], v[108:111], v[132:135], v[76:79]
	v_mfma_f32_16x16x32_bf16 v[108:111], v[178:181], v[64:67], v[60:63]
	v_mfma_f32_16x16x32_bf16 v[92:95], v[178:181], v[128:131], v[204:207]
	v_mfma_f32_16x16x32_bf16 v[100:103], v[178:181], v[132:135], v[44:47]
	v_mfma_f32_16x16x32_bf16 v[56:59], v[248:251], v[48:51], v[186:189]
	v_mfma_f32_16x16x32_bf16 v[60:63], v[248:251], v[64:67], v[224:227]
	v_mfma_f32_16x16x32_bf16 v[44:47], v[248:251], v[128:131], v[228:231]
	v_mfma_f32_16x16x32_bf16 v[72:75], v[248:251], v[132:135], v[182:185]
	v_mfma_f32_16x16x32_bf16 v[48:51], v[192:195], v[48:51], v[232:235]
	s_nop 1
	v_lshl_add_u32 v182, v68, 9, v69
	v_add_u32_e32 v183, 0x400, v182
	v_add_u32_e32 v181, 0x2000, v182
	v_mfma_f32_16x16x32_bf16 v[64:67], v[192:195], v[64:67], v[236:239]
	v_add_u32_e32 v180, 0x2400, v182
	v_add_u32_e32 v179, 0x4000, v182
	v_add_u32_e32 v178, 0x4400, v182
	v_mfma_f32_16x16x32_bf16 v[68:71], v[192:195], v[128:131], v[240:243]
	v_add_u32_e32 v175, 0x6000, v182
	v_add_u32_e32 v174, 0x6400, v182
	v_mfma_f32_16x16x32_bf16 v[76:79], v[192:195], v[132:135], v[244:247]
	s_and_saveexec_b64 s[0:1], vcc
	s_cbranch_execz .LBB0_215
	ds_write2_b32 v182, v88, v96 offset1:16
	ds_write2_b32 v182, v89, v97 offset0:128 offset1:144
	ds_write2_b32 v183, v90, v98 offset1:16
	ds_write2_b32 v183, v91, v99 offset0:128 offset1:144
	ds_write2_b32 v182, v80, v84 offset0:32 offset1:48
	ds_write2_b32 v182, v81, v85 offset0:160 offset1:176
	ds_write2_b32 v183, v82, v86 offset0:32 offset1:48
	ds_write2_b32 v183, v83, v87 offset0:160 offset1:176
	ds_write2_b32 v182, v120, v124 offset0:64 offset1:80
	ds_write2_b32 v182, v121, v125 offset0:192 offset1:208
	ds_write2_b32 v183, v122, v126 offset0:64 offset1:80
	ds_write2_b32 v183, v123, v127 offset0:192 offset1:208
	ds_write2_b32 v182, v112, v116 offset0:96 offset1:112
	ds_write2_b32 v182, v113, v117 offset0:224 offset1:240
	ds_write2_b32 v183, v114, v118 offset0:96 offset1:112
	ds_write2_b32 v183, v115, v119 offset0:224 offset1:240
	ds_write2_b32 v181, v40, v52 offset1:16
	ds_write2_b32 v181, v41, v53 offset0:128 offset1:144
	ds_write2_b32 v180, v42, v54 offset1:16
	ds_write2_b32 v180, v43, v55 offset0:128 offset1:144
	ds_write2_b32 v181, v32, v36 offset0:32 offset1:48
	ds_write2_b32 v181, v33, v37 offset0:160 offset1:176
	ds_write2_b32 v180, v34, v38 offset0:32 offset1:48
	ds_write2_b32 v180, v35, v39 offset0:160 offset1:176
	ds_write2_b32 v181, v104, v108 offset0:64 offset1:80
	ds_write2_b32 v181, v105, v109 offset0:192 offset1:208
	ds_write2_b32 v180, v106, v110 offset0:64 offset1:80
	ds_write2_b32 v180, v107, v111 offset0:192 offset1:208
	ds_write2_b32 v181, v92, v100 offset0:96 offset1:112
	ds_write2_b32 v181, v93, v101 offset0:224 offset1:240
	ds_write2_b32 v180, v94, v102 offset0:96 offset1:112
	ds_write2_b32 v180, v95, v103 offset0:224 offset1:240
	ds_write2_b32 v179, v24, v28 offset1:16
	ds_write2_b32 v179, v25, v29 offset0:128 offset1:144
	ds_write2_b32 v178, v26, v30 offset1:16
	ds_write2_b32 v178, v27, v31 offset0:128 offset1:144
	ds_write2_b32 v179, v16, v20 offset0:32 offset1:48
	ds_write2_b32 v179, v17, v21 offset0:160 offset1:176
	ds_write2_b32 v178, v18, v22 offset0:32 offset1:48
	ds_write2_b32 v178, v19, v23 offset0:160 offset1:176
	ds_write2_b32 v179, v56, v60 offset0:64 offset1:80
	ds_write2_b32 v179, v57, v61 offset0:192 offset1:208
	ds_write2_b32 v178, v58, v62 offset0:64 offset1:80
	ds_write2_b32 v178, v59, v63 offset0:192 offset1:208
	ds_write2_b32 v179, v44, v72 offset0:96 offset1:112
	ds_write2_b32 v179, v45, v73 offset0:224 offset1:240
	ds_write2_b32 v178, v46, v74 offset0:96 offset1:112
	ds_write2_b32 v178, v47, v75 offset0:224 offset1:240
	ds_write2_b32 v175, v8, v12 offset1:16
	ds_write2_b32 v175, v9, v13 offset0:128 offset1:144
	ds_write2_b32 v174, v10, v14 offset1:16
	ds_write2_b32 v174, v11, v15 offset0:128 offset1:144
	ds_write2_b32 v175, v0, v4 offset0:32 offset1:48
	ds_write2_b32 v175, v1, v5 offset0:160 offset1:176
	ds_write2_b32 v174, v2, v6 offset0:32 offset1:48
	ds_write2_b32 v174, v3, v7 offset0:160 offset1:176
	ds_write2_b32 v175, v48, v64 offset0:64 offset1:80
	ds_write2_b32 v175, v49, v65 offset0:192 offset1:208
	ds_write2_b32 v174, v50, v66 offset0:64 offset1:80
	ds_write2_b32 v174, v51, v67 offset0:192 offset1:208
	ds_write2_b32 v175, v68, v76 offset0:96 offset1:112
	ds_write2_b32 v175, v69, v77 offset0:224 offset1:240
	ds_write2_b32 v174, v70, v78 offset0:96 offset1:112
	ds_write2_b32 v174, v71, v79 offset0:224 offset1:240

.LBB0_659:
	s_add_i32 s1, s0, 0x10000
	s_and_b32 s11, s1, 0x10000
	s_waitcnt vmcnt(0)
	s_barrier
	s_and_b32 s0, s0, 0x10000
	s_add_i32 s0, s0, 0
	v_add_u32_e32 v176, s0, v148
	v_add_u32_e32 v186, v176, v147
	ds_read_b128 v[168:171], v186 offset:32768
	ds_read_b128 v[172:175], v186 offset:34816
	ds_read_b128 v[178:181], v186 offset:36864
	ds_read_b128 v[182:185], v186 offset:38912
	v_add_u32_e32 v250, v176, v146
	v_add_u32_e32 v151, s0, v149
	v_add_u32_e32 v251, v151, v146
	v_add_u32_e32 v151, v151, v147
	ds_read_b128 v[152:155], v151
	ds_read_b128 v[156:159], v151 offset:2048
	v_add_u32_e32 v254, s11, v150
	v_add_u32_e32 v228, 0x2000, v254
	v_readfirstlane_b32 s11, v254
	v_lshl_add_u64 v[188:189], v[128:129], 0, s[2:3]
	s_mov_b32 m0, s11
	v_readfirstlane_b32 s11, v228
	v_add_u32_e32 v228, 0x4000, v254
	global_load_lds_dwordx4 v[188:189], off
	v_lshl_add_u64 v[188:189], v[130:131], 0, s[2:3]
	s_mov_b32 m0, s11
	s_waitcnt lgkmcnt(1)
	v_mfma_f32_16x16x32_bf16 v[124:127], v[152:155], v[168:171], v[124:127]
	ds_read_b128 v[160:163], v151 offset:4096
	v_mfma_f32_16x16x32_bf16 v[120:123], v[152:155], v[172:175], v[120:123]
	ds_read_b128 v[164:167], v151 offset:6144
	v_readfirstlane_b32 s11, v228
	v_add_u32_e32 v228, 0x6000, v254
	v_mfma_f32_16x16x32_bf16 v[116:119], v[152:155], v[178:181], v[116:119]
	ds_read_b128 v[212:215], v186 offset:40960
	global_load_lds_dwordx4 v[188:189], off
	v_lshl_add_u64 v[188:189], v[132:133], 0, s[2:3]
	v_mfma_f32_16x16x32_bf16 v[112:115], v[152:155], v[182:185], v[112:115]
	ds_read_b128 v[216:219], v186 offset:43008
	s_mov_b32 m0, s11
	v_readfirstlane_b32 s11, v228
	s_waitcnt lgkmcnt(4)
	v_mfma_f32_16x16x32_bf16 v[104:107], v[156:159], v[168:171], v[104:107]
	ds_read_b128 v[220:223], v186 offset:45056
	global_load_lds_dwordx4 v[188:189], off
	v_lshl_add_u64 v[188:189], v[134:135], 0, s[2:3]
	v_mfma_f32_16x16x32_bf16 v[96:99], v[156:159], v[172:175], v[96:99]
	ds_read_b128 v[224:227], v186 offset:47104
	s_mov_b32 m0, s11
	v_add_u32_e32 v253, 0x8000, v254
	v_mfma_f32_16x16x32_bf16 v[88:91], v[156:159], v[178:181], v[88:91]
	ds_read_b128 v[192:195], v251
	global_load_lds_dwordx4 v[188:189], off
	v_lshl_add_u64 v[188:189], v[136:137], 0, s[2:3]
	v_mfma_f32_16x16x32_bf16 v[80:83], v[156:159], v[182:185], v[80:83]
	ds_read_b128 v[198:201], v251 offset:2048
	s_mov_b64 s[18:19], 0x550080
	v_readfirstlane_b32 s11, v253
	s_waitcnt lgkmcnt(7)
	v_mfma_f32_16x16x32_bf16 v[72:75], v[160:163], v[168:171], v[72:75]
	ds_read_b128 v[204:207], v251 offset:4096
	v_add_u32_e32 v253, 0xa000, v254
	v_lshl_add_u64 v[228:229], v[188:189], 0, s[18:19]
	v_mfma_f32_16x16x32_bf16 v[64:67], v[160:163], v[172:175], v[64:67]
	ds_read_b128 v[208:211], v251 offset:6144
	s_mov_b32 m0, s11
	s_mov_b64 s[18:19], 0x572080
	v_mfma_f32_16x16x32_bf16 v[56:59], v[160:163], v[178:181], v[56:59]
	v_readfirstlane_b32 s11, v253
	v_add_u32_e32 v253, 0xc000, v254
	v_mfma_f32_16x16x32_bf16 v[48:51], v[160:163], v[182:185], v[48:51]
	global_load_lds_dwordx4 v[228:229], off
	v_lshl_add_u64 v[228:229], v[188:189], 0, s[18:19]
	s_waitcnt lgkmcnt(8)
	v_mfma_f32_16x16x32_bf16 v[40:43], v[164:167], v[168:171], v[40:43]
	s_mov_b32 m0, s11
	s_mov_b64 s[18:19], 0x594080
	v_mfma_f32_16x16x32_bf16 v[32:35], v[164:167], v[172:175], v[32:35]
	v_readfirstlane_b32 s11, v253
	v_add_u32_e32 v254, 0xe000, v254
	v_mfma_f32_16x16x32_bf16 v[24:27], v[164:167], v[178:181], v[24:27]
	global_load_lds_dwordx4 v[228:229], off
	v_lshl_add_u64 v[228:229], v[188:189], 0, s[18:19]
	v_mfma_f32_16x16x32_bf16 v[16:19], v[164:167], v[182:185], v[16:19]
	s_mov_b32 m0, s11
	s_mov_b64 s[18:19], 0x5b6080
	s_waitcnt lgkmcnt(4)
	v_mfma_f32_16x16x32_bf16 v[100:103], v[152:155], v[212:215], v[100:103]
	v_readfirstlane_b32 s11, v254
	global_load_lds_dwordx4 v[228:229], off
	v_mfma_f32_16x16x32_bf16 v[92:95], v[152:155], v[216:219], v[92:95]
	v_lshl_add_u64 v[188:189], v[188:189], 0, s[18:19]
	s_mov_b32 m0, s11
	v_mfma_f32_16x16x32_bf16 v[84:87], v[152:155], v[220:223], v[84:87]
	ds_read_b128 v[168:171], v250 offset:32768
	global_load_lds_dwordx4 v[188:189], off
	v_mfma_f32_16x16x32_bf16 v[76:79], v[152:155], v[224:227], v[76:79]
	ds_read_b128 v[172:175], v250 offset:34816
	v_mfma_f32_16x16x32_bf16 v[68:71], v[156:159], v[212:215], v[68:71]
	ds_read_b128 v[178:181], v250 offset:36864
	v_mfma_f32_16x16x32_bf16 v[60:63], v[156:159], v[216:219], v[60:63]
	ds_read_b128 v[182:185], v250 offset:38912
	v_mfma_f32_16x16x32_bf16 v[52:55], v[156:159], v[220:223], v[52:55]
	v_mfma_f32_16x16x32_bf16 v[44:47], v[156:159], v[224:227], v[44:47]
	v_mfma_f32_16x16x32_bf16 v[36:39], v[160:163], v[212:215], v[36:39]
	v_mfma_f32_16x16x32_bf16 v[28:31], v[160:163], v[216:219], v[28:31]
	v_mfma_f32_16x16x32_bf16 v[20:23], v[160:163], v[220:223], v[20:23]
	v_mfma_f32_16x16x32_bf16 v[12:15], v[160:163], v[224:227], v[12:15]
	v_mfma_f32_16x16x32_bf16 v[8:11], v[164:167], v[212:215], v[8:11]
	v_mfma_f32_16x16x32_bf16 v[4:7], v[164:167], v[216:219], v[4:7]
	v_mfma_f32_16x16x32_bf16 v[0:3], v[164:167], v[220:223], v[0:3]
	v_mfma_f32_16x16x32_bf16 v[108:111], v[164:167], v[224:227], v[108:111]
	s_waitcnt lgkmcnt(0)
	v_mfma_f32_16x16x32_bf16 v[124:127], v[192:195], v[168:171], v[124:127]
	ds_read_b128 v[212:215], v250 offset:40960
	v_mfma_f32_16x16x32_bf16 v[120:123], v[192:195], v[172:175], v[120:123]
	ds_read_b128 v[216:219], v250 offset:43008
	v_mfma_f32_16x16x32_bf16 v[116:119], v[192:195], v[178:181], v[116:119]
	ds_read_b128 v[220:223], v250 offset:45056
	v_mfma_f32_16x16x32_bf16 v[112:115], v[192:195], v[182:185], v[112:115]
	ds_read_b128 v[224:227], v250 offset:47104
	v_mfma_f32_16x16x32_bf16 v[104:107], v[198:201], v[168:171], v[104:107]
	v_mfma_f32_16x16x32_bf16 v[96:99], v[198:201], v[172:175], v[96:99]
	v_mfma_f32_16x16x32_bf16 v[88:91], v[198:201], v[178:181], v[88:91]
	v_mfma_f32_16x16x32_bf16 v[80:83], v[198:201], v[182:185], v[80:83]
	v_mfma_f32_16x16x32_bf16 v[72:75], v[204:207], v[168:171], v[72:75]
	v_mfma_f32_16x16x32_bf16 v[64:67], v[204:207], v[172:175], v[64:67]
	v_mfma_f32_16x16x32_bf16 v[56:59], v[204:207], v[178:181], v[56:59]
	v_mfma_f32_16x16x32_bf16 v[48:51], v[204:207], v[182:185], v[48:51]
	v_mfma_f32_16x16x32_bf16 v[40:43], v[208:211], v[168:171], v[40:43]
	v_mfma_f32_16x16x32_bf16 v[32:35], v[208:211], v[172:175], v[32:35]
	v_mfma_f32_16x16x32_bf16 v[24:27], v[208:211], v[178:181], v[24:27]
	v_mfma_f32_16x16x32_bf16 v[16:19], v[208:211], v[182:185], v[16:19]
	s_waitcnt lgkmcnt(0)
	v_mfma_f32_16x16x32_bf16 v[100:103], v[192:195], v[212:215], v[100:103]
	v_mfma_f32_16x16x32_bf16 v[92:95], v[192:195], v[216:219], v[92:95]
	v_mfma_f32_16x16x32_bf16 v[84:87], v[192:195], v[220:223], v[84:87]
	v_mfma_f32_16x16x32_bf16 v[76:79], v[192:195], v[224:227], v[76:79]
	v_mfma_f32_16x16x32_bf16 v[68:71], v[198:201], v[212:215], v[68:71]
	v_mfma_f32_16x16x32_bf16 v[60:63], v[198:201], v[216:219], v[60:63]
	v_mfma_f32_16x16x32_bf16 v[52:55], v[198:201], v[220:223], v[52:55]
	v_mfma_f32_16x16x32_bf16 v[44:47], v[198:201], v[224:227], v[44:47]
	v_mfma_f32_16x16x32_bf16 v[36:39], v[204:207], v[212:215], v[36:39]
	v_mfma_f32_16x16x32_bf16 v[28:31], v[204:207], v[216:219], v[28:31]
	v_mfma_f32_16x16x32_bf16 v[20:23], v[204:207], v[220:223], v[20:23]
	v_mfma_f32_16x16x32_bf16 v[12:15], v[204:207], v[224:227], v[12:15]
	s_add_u32 s2, s2, 0x80
	s_addc_u32 s3, s3, 0
	s_cmpk_eq_i32 s2, 0x780
	s_mov_b32 s0, s1
	v_mfma_f32_16x16x32_bf16 v[8:11], v[208:211], v[212:215], v[8:11]
	v_mfma_f32_16x16x32_bf16 v[4:7], v[208:211], v[216:219], v[4:7]
	v_mfma_f32_16x16x32_bf16 v[0:3], v[208:211], v[220:223], v[0:3]
	v_mfma_f32_16x16x32_bf16 v[108:111], v[208:211], v[224:227], v[108:111]
	s_cbranch_scc0 .LBB0_659
	s_add_i32 s0, 0, 0x10000
	v_add_u32_e32 v136, s0, v149
	v_add_u32_e32 v137, v136, v147
	s_waitcnt vmcnt(0)
	s_barrier
	ds_read_b128 v[128:131], v137
	ds_read_b128 v[132:135], v137 offset:2048
	ds_read_b128 v[150:153], v137 offset:4096
	ds_read_b128 v[154:157], v137 offset:6144
	v_add_u32_e32 v137, s0, v148
	v_add_u32_e32 v147, v137, v147
	ds_read_b128 v[158:161], v147 offset:32768
	ds_read_b128 v[162:165], v147 offset:34816
	ds_read_b128 v[166:169], v147 offset:36864
	ds_read_b128 v[170:173], v147 offset:38912
	s_waitcnt lgkmcnt(0)
	v_mfma_f32_16x16x32_bf16 v[124:127], v[128:131], v[158:161], v[124:127]
	v_mfma_f32_16x16x32_bf16 v[120:123], v[128:131], v[162:165], v[120:123]
	v_mfma_f32_16x16x32_bf16 v[116:119], v[128:131], v[166:169], v[116:119]
	v_mfma_f32_16x16x32_bf16 v[112:115], v[128:131], v[170:173], v[112:115]
	v_mfma_f32_16x16x32_bf16 v[104:107], v[132:135], v[158:161], v[104:107]
	v_mfma_f32_16x16x32_bf16 v[72:75], v[150:153], v[158:161], v[72:75]
	v_mfma_f32_16x16x32_bf16 v[64:67], v[150:153], v[162:165], v[64:67]
	v_mfma_f32_16x16x32_bf16 v[56:59], v[150:153], v[166:169], v[56:59]
	v_mfma_f32_16x16x32_bf16 v[48:51], v[150:153], v[170:173], v[48:51]
	v_mfma_f32_16x16x32_bf16 v[178:181], v[132:135], v[162:165], v[96:99]
	v_mfma_f32_16x16x32_bf16 v[182:185], v[132:135], v[166:169], v[88:91]
	v_mfma_f32_16x16x32_bf16 v[186:189], v[132:135], v[170:173], v[80:83]
	v_mfma_f32_16x16x32_bf16 v[158:161], v[154:157], v[158:161], v[40:43]
	v_mfma_f32_16x16x32_bf16 v[162:165], v[154:157], v[162:165], v[32:35]
	v_mfma_f32_16x16x32_bf16 v[166:169], v[154:157], v[166:169], v[24:27]
	v_mfma_f32_16x16x32_bf16 v[170:173], v[154:157], v[170:173], v[16:19]
	s_nop 2
	ds_read_b128 v[16:19], v147 offset:40960
	ds_read_b128 v[24:27], v147 offset:43008
	ds_read_b128 v[32:35], v147 offset:45056
	ds_read_b128 v[40:43], v147 offset:47104
	s_waitcnt lgkmcnt(0)
	v_mfma_f32_16x16x32_bf16 v[100:103], v[128:131], v[16:19], v[100:103]
	v_mfma_f32_16x16x32_bf16 v[92:95], v[128:131], v[24:27], v[92:95]
	v_mfma_f32_16x16x32_bf16 v[192:195], v[128:131], v[32:35], v[84:87]
	v_mfma_f32_16x16x32_bf16 v[76:79], v[128:131], v[40:43], v[76:79]
	v_mfma_f32_16x16x32_bf16 v[68:71], v[132:135], v[16:19], v[68:71]
	v_mfma_f32_16x16x32_bf16 v[60:63], v[132:135], v[24:27], v[60:63]
	v_mfma_f32_16x16x32_bf16 v[128:131], v[132:135], v[32:35], v[52:55]
	v_mfma_f32_16x16x32_bf16 v[44:47], v[132:135], v[40:43], v[44:47]
	v_mfma_f32_16x16x32_bf16 v[132:135], v[150:153], v[16:19], v[36:39]
	v_mfma_f32_16x16x32_bf16 v[198:201], v[150:153], v[24:27], v[28:31]
	v_mfma_f32_16x16x32_bf16 v[204:207], v[150:153], v[32:35], v[20:23]
	v_mfma_f32_16x16x32_bf16 v[148:151], v[150:153], v[40:43], v[12:15]
	v_mfma_f32_16x16x32_bf16 v[208:211], v[154:157], v[16:19], v[8:11]
	v_mfma_f32_16x16x32_bf16 v[212:215], v[154:157], v[24:27], v[4:7]
	v_mfma_f32_16x16x32_bf16 v[216:219], v[154:157], v[32:35], v[0:3]
	v_mfma_f32_16x16x32_bf16 v[154:157], v[154:157], v[40:43], v[108:111]
	s_nop 1
	v_add_u32_e32 v0, v136, v146
	v_add_u32_e32 v136, v137, v146
	ds_read_b128 v[108:111], v0
	ds_read_b128 v[220:223], v0 offset:2048
	ds_read_b128 v[224:227], v0 offset:4096
	ds_read_b128 v[228:231], v0 offset:6144
	ds_read_b128 v[0:3], v136 offset:32768
	ds_read_b128 v[4:7], v136 offset:34816
	ds_read_b128 v[232:235], v136 offset:36864
	ds_read_b128 v[236:239], v136 offset:38912
	s_waitcnt lgkmcnt(0)
	v_mfma_f32_16x16x32_bf16 v[88:91], v[108:111], v[0:3], v[124:127]
	v_mfma_f32_16x16x32_bf16 v[96:99], v[108:111], v[4:7], v[120:123]
	v_mfma_f32_16x16x32_bf16 v[80:83], v[108:111], v[232:235], v[116:119]
	v_mfma_f32_16x16x32_bf16 v[84:87], v[108:111], v[236:239], v[112:115]
	v_mfma_f32_16x16x32_bf16 v[40:43], v[220:223], v[0:3], v[104:107]
	v_mfma_f32_16x16x32_bf16 v[52:55], v[220:223], v[4:7], v[178:181]
	v_mfma_f32_16x16x32_bf16 v[32:35], v[220:223], v[232:235], v[182:185]
	v_mfma_f32_16x16x32_bf16 v[36:39], v[220:223], v[236:239], v[186:189]
	v_mfma_f32_16x16x32_bf16 v[24:27], v[224:227], v[0:3], v[72:75]
	v_mfma_f32_16x16x32_bf16 v[28:31], v[224:227], v[4:7], v[64:67]
	v_mfma_f32_16x16x32_bf16 v[16:19], v[224:227], v[232:235], v[56:59]
	v_mfma_f32_16x16x32_bf16 v[20:23], v[224:227], v[236:239], v[48:51]
	v_mfma_f32_16x16x32_bf16 v[8:11], v[228:231], v[0:3], v[158:161]
	v_mfma_f32_16x16x32_bf16 v[12:15], v[228:231], v[4:7], v[162:165]
	v_mfma_f32_16x16x32_bf16 v[0:3], v[228:231], v[232:235], v[166:169]
	v_mfma_f32_16x16x32_bf16 v[4:7], v[228:231], v[236:239], v[170:173]
	ds_read_b128 v[48:51], v136 offset:40960
	ds_read_b128 v[64:67], v136 offset:43008
	ds_read_b128 v[158:161], v136 offset:45056
	ds_read_b128 v[162:165], v136 offset:47104
	s_waitcnt lgkmcnt(0)
	v_mfma_f32_16x16x32_bf16 v[104:107], v[220:223], v[48:51], v[68:71]
	v_cmp_ne_u32_e32 vcc, 0, v138
	v_cmp_eq_u32_e64 s[2:3], 0, v138
	s_waitcnt vmcnt(0)
	v_lshl_or_b32 v68, v140, 2, v141
	v_lshl_add_u32 v69, v139, 2, 0
	v_mfma_f32_16x16x32_bf16 v[120:123], v[108:111], v[48:51], v[100:103]
	v_lshl_add_u32 v152, v68, 9, v69
	v_add_u32_e32 v153, 0x400, v152
	v_add_u32_e32 v147, 0x6000, v152
	v_mfma_f32_16x16x32_bf16 v[124:127], v[108:111], v[64:67], v[92:95]
	v_add_u32_e32 v146, 0x6400, v152
	s_barrier
	v_mfma_f32_16x16x32_bf16 v[112:115], v[108:111], v[158:161], v[192:195]
	v_mfma_f32_16x16x32_bf16 v[116:119], v[108:111], v[162:165], v[76:79]
	v_mfma_f32_16x16x32_bf16 v[108:111], v[220:223], v[64:67], v[60:63]
	v_mfma_f32_16x16x32_bf16 v[92:95], v[220:223], v[158:161], v[128:131]
	v_mfma_f32_16x16x32_bf16 v[100:103], v[220:223], v[162:165], v[44:47]
	v_mfma_f32_16x16x32_bf16 v[56:59], v[224:227], v[48:51], v[132:135]
	v_mfma_f32_16x16x32_bf16 v[60:63], v[224:227], v[64:67], v[198:201]
	v_mfma_f32_16x16x32_bf16 v[44:47], v[224:227], v[158:161], v[204:207]
	v_mfma_f32_16x16x32_bf16 v[72:75], v[224:227], v[162:165], v[148:151]
	v_mfma_f32_16x16x32_bf16 v[48:51], v[228:231], v[48:51], v[208:211]
	s_nop 1
	v_add_u32_e32 v151, 0x2000, v152
	v_add_u32_e32 v150, 0x2400, v152
	v_add_u32_e32 v149, 0x4000, v152
	v_mfma_f32_16x16x32_bf16 v[64:67], v[228:231], v[64:67], v[212:215]
	v_add_u32_e32 v148, 0x4400, v152
	v_mfma_f32_16x16x32_bf16 v[68:71], v[228:231], v[158:161], v[216:219]
	v_mfma_f32_16x16x32_bf16 v[76:79], v[228:231], v[162:165], v[154:157]
	s_and_saveexec_b64 s[0:1], s[2:3]
	s_cbranch_execz .LBB0_662
	ds_write2_b32 v152, v88, v96 offset1:16
	ds_write2_b32 v152, v89, v97 offset0:128 offset1:144
	ds_write2_b32 v153, v90, v98 offset1:16
	ds_write2_b32 v153, v91, v99 offset0:128 offset1:144
	ds_write2_b32 v152, v80, v84 offset0:32 offset1:48
	ds_write2_b32 v152, v81, v85 offset0:160 offset1:176
	ds_write2_b32 v153, v82, v86 offset0:32 offset1:48
	ds_write2_b32 v153, v83, v87 offset0:160 offset1:176
	ds_write2_b32 v152, v120, v124 offset0:64 offset1:80
	ds_write2_b32 v152, v121, v125 offset0:192 offset1:208
	ds_write2_b32 v153, v122, v126 offset0:64 offset1:80
	ds_write2_b32 v153, v123, v127 offset0:192 offset1:208
	ds_write2_b32 v152, v112, v116 offset0:96 offset1:112
	ds_write2_b32 v152, v113, v117 offset0:224 offset1:240
	ds_write2_b32 v153, v114, v118 offset0:96 offset1:112
	ds_write2_b32 v153, v115, v119 offset0:224 offset1:240
	ds_write2_b32 v151, v40, v52 offset1:16
	ds_write2_b32 v151, v41, v53 offset0:128 offset1:144
	ds_write2_b32 v150, v42, v54 offset1:16
	ds_write2_b32 v150, v43, v55 offset0:128 offset1:144
	ds_write2_b32 v151, v32, v36 offset0:32 offset1:48
	ds_write2_b32 v151, v33, v37 offset0:160 offset1:176
	ds_write2_b32 v150, v34, v38 offset0:32 offset1:48
	ds_write2_b32 v150, v35, v39 offset0:160 offset1:176
	ds_write2_b32 v151, v104, v108 offset0:64 offset1:80
	ds_write2_b32 v151, v105, v109 offset0:192 offset1:208
	ds_write2_b32 v150, v106, v110 offset0:64 offset1:80
	ds_write2_b32 v150, v107, v111 offset0:192 offset1:208
	ds_write2_b32 v151, v92, v100 offset0:96 offset1:112
	ds_write2_b32 v151, v93, v101 offset0:224 offset1:240
	ds_write2_b32 v150, v94, v102 offset0:96 offset1:112
	ds_write2_b32 v150, v95, v103 offset0:224 offset1:240
	ds_write2_b32 v149, v24, v28 offset1:16
	ds_write2_b32 v149, v25, v29 offset0:128 offset1:144
	ds_write2_b32 v148, v26, v30 offset1:16
	ds_write2_b32 v148, v27, v31 offset0:128 offset1:144
	ds_write2_b32 v149, v16, v20 offset0:32 offset1:48
	ds_write2_b32 v149, v17, v21 offset0:160 offset1:176
	ds_write2_b32 v148, v18, v22 offset0:32 offset1:48
	ds_write2_b32 v148, v19, v23 offset0:160 offset1:176
	ds_write2_b32 v149, v56, v60 offset0:64 offset1:80
	ds_write2_b32 v149, v57, v61 offset0:192 offset1:208
	ds_write2_b32 v148, v58, v62 offset0:64 offset1:80
	ds_write2_b32 v148, v59, v63 offset0:192 offset1:208
	ds_write2_b32 v149, v44, v72 offset0:96 offset1:112
	ds_write2_b32 v149, v45, v73 offset0:224 offset1:240
	ds_write2_b32 v148, v46, v74 offset0:96 offset1:112
	ds_write2_b32 v148, v47, v75 offset0:224 offset1:240
	ds_write2_b32 v147, v8, v12 offset1:16
	ds_write2_b32 v147, v9, v13 offset0:128 offset1:144
	ds_write2_b32 v146, v10, v14 offset1:16
	ds_write2_b32 v146, v11, v15 offset0:128 offset1:144
	ds_write2_b32 v147, v0, v4 offset0:32 offset1:48
	ds_write2_b32 v147, v1, v5 offset0:160 offset1:176
	ds_write2_b32 v146, v2, v6 offset0:32 offset1:48
	ds_write2_b32 v146, v3, v7 offset0:160 offset1:176
	ds_write2_b32 v147, v48, v64 offset0:64 offset1:80
	ds_write2_b32 v147, v49, v65 offset0:192 offset1:208
	ds_write2_b32 v146, v50, v66 offset0:64 offset1:80
	ds_write2_b32 v146, v51, v67 offset0:192 offset1:208
	ds_write2_b32 v147, v68, v76 offset0:96 offset1:112
	ds_write2_b32 v147, v69, v77 offset0:224 offset1:240
	ds_write2_b32 v146, v70, v78 offset0:96 offset1:112
	ds_write2_b32 v146, v71, v79 offset0:224 offset1:240

.LBB0_1074:
	s_add_i32 s5, s4, 0x10000
	s_and_b32 s40, s5, 0x10000
	s_waitcnt vmcnt(0)
	s_barrier
	s_and_b32 s4, s4, 0x10000
	s_add_i32 s4, s4, 0
	v_add_u32_e32 v160, s4, v145
	v_add_u32_e32 v161, v160, v143
	ds_read_b128 v[178:181], v161 offset:32768
	ds_read_b128 v[182:185], v161 offset:34816
	ds_read_b128 v[186:189], v161 offset:36864
	ds_read_b128 v[192:195], v161 offset:38912
	v_add_u32_e32 v250, v160, v142
	v_add_u32_e32 v147, s4, v144
	v_add_u32_e32 v251, v147, v142
	v_add_u32_e32 v147, v147, v143
	ds_read_b128 v[148:151], v147
	ds_read_b128 v[152:155], v147 offset:2048
	v_add_u32_e32 v254, s40, v146
	v_add_u32_e32 v232, 0x2000, v254
	v_readfirstlane_b32 s40, v254
	v_lshl_add_u64 v[174:175], v[136:137], 0, s[2:3]
	s_mov_b32 m0, s40
	v_readfirstlane_b32 s40, v232
	v_add_u32_e32 v232, 0x4000, v254
	global_load_lds_dwordx4 v[174:175], off
	v_lshl_add_u64 v[174:175], v[134:135], 0, s[2:3]
	s_mov_b32 m0, s40
	s_waitcnt lgkmcnt(1)
	v_mfma_f32_16x16x32_bf16 v[124:127], v[148:151], v[178:181], v[124:127]
	ds_read_b128 v[156:159], v147 offset:4096
	v_mfma_f32_16x16x32_bf16 v[120:123], v[148:151], v[182:185], v[120:123]
	ds_read_b128 v[170:173], v147 offset:6144
	v_readfirstlane_b32 s40, v232
	v_add_u32_e32 v232, 0x6000, v254
	v_mfma_f32_16x16x32_bf16 v[116:119], v[148:151], v[186:189], v[116:119]
	ds_read_b128 v[216:219], v161 offset:40960
	global_load_lds_dwordx4 v[174:175], off
	v_lshl_add_u64 v[174:175], v[132:133], 0, s[2:3]
	v_mfma_f32_16x16x32_bf16 v[112:115], v[148:151], v[192:195], v[112:115]
	ds_read_b128 v[220:223], v161 offset:43008
	s_mov_b32 m0, s40
	v_readfirstlane_b32 s40, v232
	s_waitcnt lgkmcnt(4)
	v_mfma_f32_16x16x32_bf16 v[104:107], v[152:155], v[178:181], v[104:107]
	ds_read_b128 v[224:227], v161 offset:45056
	global_load_lds_dwordx4 v[174:175], off
	v_lshl_add_u64 v[174:175], v[130:131], 0, s[2:3]
	v_mfma_f32_16x16x32_bf16 v[96:99], v[152:155], v[182:185], v[96:99]
	ds_read_b128 v[228:231], v161 offset:47104
	s_mov_b32 m0, s40
	s_mov_b64 s[40:41], 0x770080
	v_mfma_f32_16x16x32_bf16 v[88:91], v[152:155], v[186:189], v[88:91]
	ds_read_b128 v[198:201], v251
	global_load_lds_dwordx4 v[174:175], off
	v_lshl_add_u64 v[174:175], v[128:129], 0, s[2:3]
	v_mfma_f32_16x16x32_bf16 v[80:83], v[152:155], v[192:195], v[80:83]
	ds_read_b128 v[204:207], v251 offset:2048
	v_add_u32_e32 v253, 0x8000, v254
	v_lshl_add_u64 v[232:233], v[174:175], 0, s[40:41]
	s_waitcnt lgkmcnt(7)
	v_mfma_f32_16x16x32_bf16 v[72:75], v[156:159], v[178:181], v[72:75]
	ds_read_b128 v[208:211], v251 offset:4096
	v_readfirstlane_b32 s40, v253
	s_mov_b32 m0, s40
	v_mfma_f32_16x16x32_bf16 v[64:67], v[156:159], v[182:185], v[64:67]
	ds_read_b128 v[212:215], v251 offset:6144
	s_mov_b64 s[40:41], 0x792080
	v_add_u32_e32 v253, 0xa000, v254
	v_mfma_f32_16x16x32_bf16 v[56:59], v[156:159], v[186:189], v[56:59]
	global_load_lds_dwordx4 v[232:233], off
	v_lshl_add_u64 v[232:233], v[174:175], 0, s[40:41]
	v_mfma_f32_16x16x32_bf16 v[48:51], v[156:159], v[192:195], v[48:51]
	v_readfirstlane_b32 s40, v253
	s_mov_b32 m0, s40
	s_waitcnt lgkmcnt(8)
	v_mfma_f32_16x16x32_bf16 v[40:43], v[170:173], v[178:181], v[40:43]
	s_mov_b64 s[40:41], 0x7b4080
	v_add_u32_e32 v253, 0xc000, v254
	v_mfma_f32_16x16x32_bf16 v[32:35], v[170:173], v[182:185], v[32:35]
	global_load_lds_dwordx4 v[232:233], off
	v_lshl_add_u64 v[232:233], v[174:175], 0, s[40:41]
	v_mfma_f32_16x16x32_bf16 v[24:27], v[170:173], v[186:189], v[24:27]
	v_readfirstlane_b32 s40, v253
	s_mov_b32 m0, s40
	v_mfma_f32_16x16x32_bf16 v[16:19], v[170:173], v[192:195], v[16:19]
	s_mov_b64 s[40:41], 0x7d6080
	v_add_u32_e32 v254, 0xe000, v254
	s_waitcnt lgkmcnt(4)
	v_mfma_f32_16x16x32_bf16 v[100:103], v[148:151], v[216:219], v[100:103]
	v_lshl_add_u64 v[174:175], v[174:175], 0, s[40:41]
	v_readfirstlane_b32 s40, v254
	v_mfma_f32_16x16x32_bf16 v[92:95], v[148:151], v[220:223], v[92:95]
	global_load_lds_dwordx4 v[232:233], off
	s_mov_b32 m0, s40
	v_mfma_f32_16x16x32_bf16 v[84:87], v[148:151], v[224:227], v[84:87]
	ds_read_b128 v[178:181], v250 offset:32768
	global_load_lds_dwordx4 v[174:175], off
	v_mfma_f32_16x16x32_bf16 v[76:79], v[148:151], v[228:231], v[76:79]
	ds_read_b128 v[182:185], v250 offset:34816
	v_mfma_f32_16x16x32_bf16 v[68:71], v[152:155], v[216:219], v[68:71]
	ds_read_b128 v[186:189], v250 offset:36864
	v_mfma_f32_16x16x32_bf16 v[60:63], v[152:155], v[220:223], v[60:63]
	ds_read_b128 v[192:195], v250 offset:38912
	v_mfma_f32_16x16x32_bf16 v[52:55], v[152:155], v[224:227], v[52:55]
	v_mfma_f32_16x16x32_bf16 v[44:47], v[152:155], v[228:231], v[44:47]
	v_mfma_f32_16x16x32_bf16 v[36:39], v[156:159], v[216:219], v[36:39]
	v_mfma_f32_16x16x32_bf16 v[28:31], v[156:159], v[220:223], v[28:31]
	v_mfma_f32_16x16x32_bf16 v[20:23], v[156:159], v[224:227], v[20:23]
	v_mfma_f32_16x16x32_bf16 v[12:15], v[156:159], v[228:231], v[12:15]
	v_mfma_f32_16x16x32_bf16 v[8:11], v[170:173], v[216:219], v[8:11]
	v_mfma_f32_16x16x32_bf16 v[4:7], v[170:173], v[220:223], v[4:7]
	v_mfma_f32_16x16x32_bf16 v[0:3], v[170:173], v[224:227], v[0:3]
	v_mfma_f32_16x16x32_bf16 v[108:111], v[170:173], v[228:231], v[108:111]
	s_waitcnt lgkmcnt(0)
	v_mfma_f32_16x16x32_bf16 v[124:127], v[198:201], v[178:181], v[124:127]
	ds_read_b128 v[216:219], v250 offset:40960
	v_mfma_f32_16x16x32_bf16 v[120:123], v[198:201], v[182:185], v[120:123]
	ds_read_b128 v[220:223], v250 offset:43008
	v_mfma_f32_16x16x32_bf16 v[116:119], v[198:201], v[186:189], v[116:119]
	ds_read_b128 v[224:227], v250 offset:45056
	v_mfma_f32_16x16x32_bf16 v[112:115], v[198:201], v[192:195], v[112:115]
	ds_read_b128 v[228:231], v250 offset:47104
	v_mfma_f32_16x16x32_bf16 v[104:107], v[204:207], v[178:181], v[104:107]
	v_mfma_f32_16x16x32_bf16 v[96:99], v[204:207], v[182:185], v[96:99]
	v_mfma_f32_16x16x32_bf16 v[88:91], v[204:207], v[186:189], v[88:91]
	v_mfma_f32_16x16x32_bf16 v[80:83], v[204:207], v[192:195], v[80:83]
	v_mfma_f32_16x16x32_bf16 v[72:75], v[208:211], v[178:181], v[72:75]
	v_mfma_f32_16x16x32_bf16 v[64:67], v[208:211], v[182:185], v[64:67]
	v_mfma_f32_16x16x32_bf16 v[56:59], v[208:211], v[186:189], v[56:59]
	v_mfma_f32_16x16x32_bf16 v[48:51], v[208:211], v[192:195], v[48:51]
	v_mfma_f32_16x16x32_bf16 v[40:43], v[212:215], v[178:181], v[40:43]
	v_mfma_f32_16x16x32_bf16 v[32:35], v[212:215], v[182:185], v[32:35]
	v_mfma_f32_16x16x32_bf16 v[24:27], v[212:215], v[186:189], v[24:27]
	v_mfma_f32_16x16x32_bf16 v[16:19], v[212:215], v[192:195], v[16:19]
	s_waitcnt lgkmcnt(0)
	v_mfma_f32_16x16x32_bf16 v[100:103], v[198:201], v[216:219], v[100:103]
	v_mfma_f32_16x16x32_bf16 v[92:95], v[198:201], v[220:223], v[92:95]
	v_mfma_f32_16x16x32_bf16 v[84:87], v[198:201], v[224:227], v[84:87]
	v_mfma_f32_16x16x32_bf16 v[76:79], v[198:201], v[228:231], v[76:79]
	v_mfma_f32_16x16x32_bf16 v[68:71], v[204:207], v[216:219], v[68:71]
	v_mfma_f32_16x16x32_bf16 v[60:63], v[204:207], v[220:223], v[60:63]
	v_mfma_f32_16x16x32_bf16 v[52:55], v[204:207], v[224:227], v[52:55]
	v_mfma_f32_16x16x32_bf16 v[44:47], v[204:207], v[228:231], v[44:47]
	v_mfma_f32_16x16x32_bf16 v[36:39], v[208:211], v[216:219], v[36:39]
	v_mfma_f32_16x16x32_bf16 v[28:31], v[208:211], v[220:223], v[28:31]
	v_mfma_f32_16x16x32_bf16 v[20:23], v[208:211], v[224:227], v[20:23]
	v_mfma_f32_16x16x32_bf16 v[12:15], v[208:211], v[228:231], v[12:15]
	s_add_u32 s2, s2, 0x80
	s_addc_u32 s3, s3, 0
	s_cmpk_eq_i32 s2, 0x780
	s_mov_b32 s4, s5
	v_mfma_f32_16x16x32_bf16 v[8:11], v[212:215], v[216:219], v[8:11]
	v_mfma_f32_16x16x32_bf16 v[4:7], v[212:215], v[220:223], v[4:7]
	v_mfma_f32_16x16x32_bf16 v[0:3], v[212:215], v[224:227], v[0:3]
	v_mfma_f32_16x16x32_bf16 v[108:111], v[212:215], v[228:231], v[108:111]
	s_cbranch_scc0 .LBB0_1074
	s_add_i32 s2, 0, 0x10000
	v_add_u32_e32 v136, s2, v145
	v_add_u32_e32 v174, s2, v144
	v_add_u32_e32 v137, v136, v143
	v_add_u32_e32 v143, v174, v143
	s_waitcnt vmcnt(0)
	s_barrier
	ds_read_b128 v[128:131], v137 offset:38912
	ds_read_b128 v[132:135], v137 offset:36864
	ds_read_b128 v[146:149], v137 offset:34816
	ds_read_b128 v[150:153], v137 offset:32768
	ds_read_b128 v[154:157], v143 offset:6144
	ds_read_b128 v[158:161], v143 offset:4096
	ds_read_b128 v[170:173], v143 offset:2048
	ds_read_b128 v[178:181], v143
	s_waitcnt lgkmcnt(0)
	v_mfma_f32_16x16x32_bf16 v[124:127], v[178:181], v[150:153], v[124:127]
	v_mfma_f32_16x16x32_bf16 v[120:123], v[178:181], v[146:149], v[120:123]
	v_mfma_f32_16x16x32_bf16 v[116:119], v[178:181], v[132:135], v[116:119]
	v_mfma_f32_16x16x32_bf16 v[112:115], v[178:181], v[128:131], v[112:115]
	v_mfma_f32_16x16x32_bf16 v[104:107], v[170:173], v[150:153], v[104:107]
	v_mfma_f32_16x16x32_bf16 v[72:75], v[158:161], v[150:153], v[72:75]
	v_mfma_f32_16x16x32_bf16 v[64:67], v[158:161], v[146:149], v[64:67]
	v_mfma_f32_16x16x32_bf16 v[56:59], v[158:161], v[132:135], v[56:59]
	v_mfma_f32_16x16x32_bf16 v[48:51], v[158:161], v[128:131], v[48:51]
	v_mfma_f32_16x16x32_bf16 v[182:185], v[170:173], v[146:149], v[96:99]
	v_mfma_f32_16x16x32_bf16 v[186:189], v[170:173], v[132:135], v[88:91]
	v_mfma_f32_16x16x32_bf16 v[192:195], v[170:173], v[128:131], v[80:83]
	v_mfma_f32_16x16x32_bf16 v[150:153], v[154:157], v[150:153], v[40:43]
	v_mfma_f32_16x16x32_bf16 v[144:147], v[154:157], v[146:149], v[32:35]
	v_mfma_f32_16x16x32_bf16 v[132:135], v[154:157], v[132:135], v[24:27]
	v_mfma_f32_16x16x32_bf16 v[128:131], v[154:157], v[128:131], v[16:19]
	s_nop 2
	ds_read_b128 v[16:19], v137 offset:40960
	ds_read_b128 v[24:27], v137 offset:43008
	ds_read_b128 v[32:35], v137 offset:45056
	ds_read_b128 v[40:43], v137 offset:47104
	s_waitcnt lgkmcnt(0)
	v_mfma_f32_16x16x32_bf16 v[100:103], v[178:181], v[16:19], v[100:103]
	v_mfma_f32_16x16x32_bf16 v[92:95], v[178:181], v[24:27], v[92:95]
	v_mfma_f32_16x16x32_bf16 v[198:201], v[178:181], v[32:35], v[84:87]
	v_mfma_f32_16x16x32_bf16 v[76:79], v[178:181], v[40:43], v[76:79]
	v_mfma_f32_16x16x32_bf16 v[68:71], v[170:173], v[16:19], v[68:71]
	v_mfma_f32_16x16x32_bf16 v[60:63], v[170:173], v[24:27], v[60:63]
	v_mfma_f32_16x16x32_bf16 v[178:181], v[170:173], v[32:35], v[52:55]
	v_mfma_f32_16x16x32_bf16 v[44:47], v[170:173], v[40:43], v[44:47]
	v_mfma_f32_16x16x32_bf16 v[170:173], v[158:161], v[16:19], v[36:39]
	v_mfma_f32_16x16x32_bf16 v[204:207], v[158:161], v[24:27], v[28:31]
	v_mfma_f32_16x16x32_bf16 v[208:211], v[158:161], v[32:35], v[20:23]
	v_mfma_f32_16x16x32_bf16 v[158:161], v[158:161], v[40:43], v[12:15]
	v_mfma_f32_16x16x32_bf16 v[212:215], v[154:157], v[16:19], v[8:11]
	v_mfma_f32_16x16x32_bf16 v[216:219], v[154:157], v[24:27], v[4:7]
	v_mfma_f32_16x16x32_bf16 v[220:223], v[154:157], v[32:35], v[0:3]
	v_mfma_f32_16x16x32_bf16 v[154:157], v[154:157], v[40:43], v[108:111]
	s_nop 1
	v_add_u32_e32 v0, v174, v142
	v_add_u32_e32 v136, v136, v142
	ds_read_b128 v[108:111], v0
	ds_read_b128 v[224:227], v0 offset:2048
	ds_read_b128 v[228:231], v0 offset:4096
	ds_read_b128 v[232:235], v0 offset:6144
	ds_read_b128 v[0:3], v136 offset:32768
	ds_read_b128 v[4:7], v136 offset:34816
	ds_read_b128 v[236:239], v136 offset:36864
	ds_read_b128 v[240:243], v136 offset:38912
	s_waitcnt lgkmcnt(0)
	v_mfma_f32_16x16x32_bf16 v[88:91], v[108:111], v[0:3], v[124:127]
	v_mfma_f32_16x16x32_bf16 v[96:99], v[108:111], v[4:7], v[120:123]
	v_mfma_f32_16x16x32_bf16 v[80:83], v[108:111], v[236:239], v[116:119]
	v_mfma_f32_16x16x32_bf16 v[84:87], v[108:111], v[240:243], v[112:115]
	v_mfma_f32_16x16x32_bf16 v[40:43], v[224:227], v[0:3], v[104:107]
	v_mfma_f32_16x16x32_bf16 v[52:55], v[224:227], v[4:7], v[182:185]
	v_mfma_f32_16x16x32_bf16 v[32:35], v[224:227], v[236:239], v[186:189]
	v_mfma_f32_16x16x32_bf16 v[36:39], v[224:227], v[240:243], v[192:195]
	v_mfma_f32_16x16x32_bf16 v[24:27], v[228:231], v[0:3], v[72:75]
	v_mfma_f32_16x16x32_bf16 v[28:31], v[228:231], v[4:7], v[64:67]
	v_mfma_f32_16x16x32_bf16 v[16:19], v[228:231], v[236:239], v[56:59]
	v_mfma_f32_16x16x32_bf16 v[20:23], v[228:231], v[240:243], v[48:51]
	v_mfma_f32_16x16x32_bf16 v[8:11], v[232:235], v[0:3], v[150:153]
	v_mfma_f32_16x16x32_bf16 v[12:15], v[232:235], v[4:7], v[144:147]
	v_mfma_f32_16x16x32_bf16 v[0:3], v[232:235], v[236:239], v[132:135]
	v_mfma_f32_16x16x32_bf16 v[4:7], v[232:235], v[240:243], v[128:131]
	ds_read_b128 v[48:51], v136 offset:40960
	ds_read_b128 v[64:67], v136 offset:43008
	s_nop 0
	ds_read_b128 v[128:131], v136 offset:45056
	ds_read_b128 v[132:135], v136 offset:47104
	s_waitcnt lgkmcnt(0)
	v_mfma_f32_16x16x32_bf16 v[104:107], v[224:227], v[48:51], v[68:71]
	v_cmp_ne_u32_e32 vcc, 0, v138
	v_cmp_eq_u32_e64 s[2:3], 0, v138
	s_waitcnt vmcnt(0)
	v_lshl_or_b32 v68, v140, 2, v141
	v_lshl_add_u32 v69, v139, 2, 0
	v_mfma_f32_16x16x32_bf16 v[120:123], v[108:111], v[48:51], v[100:103]
	s_barrier
	v_mfma_f32_16x16x32_bf16 v[124:127], v[108:111], v[64:67], v[92:95]
	v_mfma_f32_16x16x32_bf16 v[112:115], v[108:111], v[128:131], v[198:201]
	v_mfma_f32_16x16x32_bf16 v[116:119], v[108:111], v[132:135], v[76:79]
	v_mfma_f32_16x16x32_bf16 v[108:111], v[224:227], v[64:67], v[60:63]
	v_mfma_f32_16x16x32_bf16 v[92:95], v[224:227], v[128:131], v[178:181]
	v_mfma_f32_16x16x32_bf16 v[100:103], v[224:227], v[132:135], v[44:47]
	s_nop 1
	v_lshl_add_u32 v178, v68, 9, v69
	v_add_u32_e32 v179, 0x400, v178
	v_add_u32_e32 v176, 0x2000, v178
	v_mfma_f32_16x16x32_bf16 v[56:59], v[228:231], v[48:51], v[170:173]
	v_add_u32_e32 v175, 0x2400, v178
	v_add_u32_e32 v174, 0x4000, v178
	v_mfma_f32_16x16x32_bf16 v[60:63], v[228:231], v[64:67], v[204:207]
	v_add_u32_e32 v173, 0x4400, v178
	v_add_u32_e32 v172, 0x6000, v178
	v_add_u32_e32 v171, 0x6400, v178
	v_mfma_f32_16x16x32_bf16 v[44:47], v[228:231], v[128:131], v[208:211]
	v_mfma_f32_16x16x32_bf16 v[72:75], v[228:231], v[132:135], v[158:161]
	v_mfma_f32_16x16x32_bf16 v[48:51], v[232:235], v[48:51], v[212:215]
	v_mfma_f32_16x16x32_bf16 v[64:67], v[232:235], v[64:67], v[216:219]
	v_mfma_f32_16x16x32_bf16 v[68:71], v[232:235], v[128:131], v[220:223]
	v_mfma_f32_16x16x32_bf16 v[76:79], v[232:235], v[132:135], v[154:157]
	s_and_saveexec_b64 s[4:5], s[2:3]
	s_cbranch_execz .LBB0_1077
	ds_write2_b32 v178, v88, v96 offset1:16
	ds_write2_b32 v178, v89, v97 offset0:128 offset1:144
	ds_write2_b32 v179, v90, v98 offset1:16
	ds_write2_b32 v179, v91, v99 offset0:128 offset1:144
	ds_write2_b32 v178, v80, v84 offset0:32 offset1:48
	ds_write2_b32 v178, v81, v85 offset0:160 offset1:176
	ds_write2_b32 v179, v82, v86 offset0:32 offset1:48
	ds_write2_b32 v179, v83, v87 offset0:160 offset1:176
	ds_write2_b32 v178, v120, v124 offset0:64 offset1:80
	ds_write2_b32 v178, v121, v125 offset0:192 offset1:208
	ds_write2_b32 v179, v122, v126 offset0:64 offset1:80
	ds_write2_b32 v179, v123, v127 offset0:192 offset1:208
	ds_write2_b32 v178, v112, v116 offset0:96 offset1:112
	ds_write2_b32 v178, v113, v117 offset0:224 offset1:240
	ds_write2_b32 v179, v114, v118 offset0:96 offset1:112
	ds_write2_b32 v179, v115, v119 offset0:224 offset1:240
	ds_write2_b32 v176, v40, v52 offset1:16
	ds_write2_b32 v176, v41, v53 offset0:128 offset1:144
	ds_write2_b32 v175, v42, v54 offset1:16
	ds_write2_b32 v175, v43, v55 offset0:128 offset1:144
	ds_write2_b32 v176, v32, v36 offset0:32 offset1:48
	ds_write2_b32 v176, v33, v37 offset0:160 offset1:176
	ds_write2_b32 v175, v34, v38 offset0:32 offset1:48
	ds_write2_b32 v175, v35, v39 offset0:160 offset1:176
	ds_write2_b32 v176, v104, v108 offset0:64 offset1:80
	ds_write2_b32 v176, v105, v109 offset0:192 offset1:208
	ds_write2_b32 v175, v106, v110 offset0:64 offset1:80
	ds_write2_b32 v175, v107, v111 offset0:192 offset1:208
	ds_write2_b32 v176, v92, v100 offset0:96 offset1:112
	ds_write2_b32 v176, v93, v101 offset0:224 offset1:240
	ds_write2_b32 v175, v94, v102 offset0:96 offset1:112
	ds_write2_b32 v175, v95, v103 offset0:224 offset1:240
	ds_write2_b32 v174, v24, v28 offset1:16
	ds_write2_b32 v174, v25, v29 offset0:128 offset1:144
	ds_write2_b32 v173, v26, v30 offset1:16
	ds_write2_b32 v173, v27, v31 offset0:128 offset1:144
	ds_write2_b32 v174, v16, v20 offset0:32 offset1:48
	ds_write2_b32 v174, v17, v21 offset0:160 offset1:176
	ds_write2_b32 v173, v18, v22 offset0:32 offset1:48
	ds_write2_b32 v173, v19, v23 offset0:160 offset1:176
	ds_write2_b32 v174, v56, v60 offset0:64 offset1:80
	ds_write2_b32 v174, v57, v61 offset0:192 offset1:208
	ds_write2_b32 v173, v58, v62 offset0:64 offset1:80
	ds_write2_b32 v173, v59, v63 offset0:192 offset1:208
	ds_write2_b32 v174, v44, v72 offset0:96 offset1:112
	ds_write2_b32 v174, v45, v73 offset0:224 offset1:240
	ds_write2_b32 v173, v46, v74 offset0:96 offset1:112
	ds_write2_b32 v173, v47, v75 offset0:224 offset1:240
	ds_write2_b32 v172, v8, v12 offset1:16
	ds_write2_b32 v172, v9, v13 offset0:128 offset1:144
	ds_write2_b32 v171, v10, v14 offset1:16
	ds_write2_b32 v171, v11, v15 offset0:128 offset1:144
	ds_write2_b32 v172, v0, v4 offset0:32 offset1:48
	ds_write2_b32 v172, v1, v5 offset0:160 offset1:176
	ds_write2_b32 v171, v2, v6 offset0:32 offset1:48
	ds_write2_b32 v171, v3, v7 offset0:160 offset1:176
	ds_write2_b32 v172, v48, v64 offset0:64 offset1:80
	ds_write2_b32 v172, v49, v65 offset0:192 offset1:208
	ds_write2_b32 v171, v50, v66 offset0:64 offset1:80
	ds_write2_b32 v171, v51, v67 offset0:192 offset1:208
	ds_write2_b32 v172, v68, v76 offset0:96 offset1:112
	ds_write2_b32 v172, v69, v77 offset0:224 offset1:240
	ds_write2_b32 v171, v70, v78 offset0:96 offset1:112
	ds_write2_b32 v171, v71, v79 offset0:224 offset1:240

.LBB0_1143:
	s_add_i32 s11, s10, 0x10000
	s_and_b32 s19, s11, 0x10000
	s_waitcnt vmcnt(0)
	s_barrier
	s_and_b32 s10, s10, 0x10000
	s_add_i32 s10, s10, 0
	v_add_u32_e32 v176, s10, v148
	v_add_u32_e32 v186, v176, v147
	ds_read_b128 v[168:171], v186 offset:32768
	ds_read_b128 v[172:175], v186 offset:34816
	ds_read_b128 v[178:181], v186 offset:36864
	ds_read_b128 v[182:185], v186 offset:38912
	v_add_u32_e32 v250, v176, v146
	v_add_u32_e32 v151, s10, v149
	v_add_u32_e32 v251, v151, v146
	v_add_u32_e32 v151, v151, v147
	ds_read_b128 v[152:155], v151
	ds_read_b128 v[156:159], v151 offset:2048
	v_add_u32_e32 v254, s19, v150
	v_add_u32_e32 v228, 0x2000, v254
	v_readfirstlane_b32 s19, v254
	v_lshl_add_u64 v[188:189], v[128:129], 0, s[2:3]
	s_mov_b32 m0, s19
	v_readfirstlane_b32 s19, v228
	v_add_u32_e32 v228, 0x4000, v254
	global_load_lds_dwordx4 v[188:189], off
	v_lshl_add_u64 v[188:189], v[130:131], 0, s[2:3]
	s_mov_b32 m0, s19
	s_waitcnt lgkmcnt(1)
	v_mfma_f32_16x16x32_bf16 v[124:127], v[152:155], v[168:171], v[124:127]
	ds_read_b128 v[160:163], v151 offset:4096
	v_mfma_f32_16x16x32_bf16 v[120:123], v[152:155], v[172:175], v[120:123]
	ds_read_b128 v[164:167], v151 offset:6144
	v_readfirstlane_b32 s19, v228
	v_add_u32_e32 v228, 0x6000, v254
	v_mfma_f32_16x16x32_bf16 v[116:119], v[152:155], v[178:181], v[116:119]
	ds_read_b128 v[212:215], v186 offset:40960
	global_load_lds_dwordx4 v[188:189], off
	v_lshl_add_u64 v[188:189], v[132:133], 0, s[2:3]
	v_mfma_f32_16x16x32_bf16 v[112:115], v[152:155], v[182:185], v[112:115]
	ds_read_b128 v[216:219], v186 offset:43008
	s_mov_b32 m0, s19
	v_readfirstlane_b32 s19, v228
	s_waitcnt lgkmcnt(4)
	v_mfma_f32_16x16x32_bf16 v[104:107], v[156:159], v[168:171], v[104:107]
	ds_read_b128 v[220:223], v186 offset:45056
	global_load_lds_dwordx4 v[188:189], off
	v_lshl_add_u64 v[188:189], v[134:135], 0, s[2:3]
	v_mfma_f32_16x16x32_bf16 v[96:99], v[156:159], v[172:175], v[96:99]
	ds_read_b128 v[224:227], v186 offset:47104
	s_mov_b32 m0, s19
	v_add_u32_e32 v253, 0x8000, v254
	v_mfma_f32_16x16x32_bf16 v[88:91], v[156:159], v[178:181], v[88:91]
	ds_read_b128 v[192:195], v251
	global_load_lds_dwordx4 v[188:189], off
	v_lshl_add_u64 v[188:189], v[136:137], 0, s[2:3]
	v_mfma_f32_16x16x32_bf16 v[80:83], v[156:159], v[182:185], v[80:83]
	ds_read_b128 v[198:201], v251 offset:2048
	s_mov_b64 s[20:21], 0x1320080
	v_readfirstlane_b32 s19, v253
	s_waitcnt lgkmcnt(7)
	v_mfma_f32_16x16x32_bf16 v[72:75], v[160:163], v[168:171], v[72:75]
	ds_read_b128 v[204:207], v251 offset:4096
	v_add_u32_e32 v253, 0xa000, v254
	v_lshl_add_u64 v[228:229], v[188:189], 0, s[20:21]
	v_mfma_f32_16x16x32_bf16 v[64:67], v[160:163], v[172:175], v[64:67]
	ds_read_b128 v[208:211], v251 offset:6144
	s_mov_b32 m0, s19
	s_mov_b64 s[20:21], 0x1378080
	v_mfma_f32_16x16x32_bf16 v[56:59], v[160:163], v[178:181], v[56:59]
	v_readfirstlane_b32 s19, v253
	v_add_u32_e32 v253, 0xc000, v254
	v_mfma_f32_16x16x32_bf16 v[48:51], v[160:163], v[182:185], v[48:51]
	global_load_lds_dwordx4 v[228:229], off
	v_lshl_add_u64 v[228:229], v[188:189], 0, s[20:21]
	s_waitcnt lgkmcnt(8)
	v_mfma_f32_16x16x32_bf16 v[40:43], v[164:167], v[168:171], v[40:43]
	s_mov_b32 m0, s19
	s_mov_b64 s[20:21], 0x13d0080
	v_mfma_f32_16x16x32_bf16 v[32:35], v[164:167], v[172:175], v[32:35]
	v_readfirstlane_b32 s19, v253
	v_add_u32_e32 v254, 0xe000, v254
	v_mfma_f32_16x16x32_bf16 v[24:27], v[164:167], v[178:181], v[24:27]
	global_load_lds_dwordx4 v[228:229], off
	v_lshl_add_u64 v[228:229], v[188:189], 0, s[20:21]
	v_mfma_f32_16x16x32_bf16 v[16:19], v[164:167], v[182:185], v[16:19]
	s_mov_b32 m0, s19
	s_mov_b64 s[20:21], 0x1428080
	s_waitcnt lgkmcnt(4)
	v_mfma_f32_16x16x32_bf16 v[100:103], v[152:155], v[212:215], v[100:103]
	v_readfirstlane_b32 s19, v254
	global_load_lds_dwordx4 v[228:229], off
	v_mfma_f32_16x16x32_bf16 v[92:95], v[152:155], v[216:219], v[92:95]
	v_lshl_add_u64 v[188:189], v[188:189], 0, s[20:21]
	s_mov_b32 m0, s19
	v_mfma_f32_16x16x32_bf16 v[84:87], v[152:155], v[220:223], v[84:87]
	ds_read_b128 v[168:171], v250 offset:32768
	global_load_lds_dwordx4 v[188:189], off
	v_mfma_f32_16x16x32_bf16 v[76:79], v[152:155], v[224:227], v[76:79]
	ds_read_b128 v[172:175], v250 offset:34816
	v_mfma_f32_16x16x32_bf16 v[68:71], v[156:159], v[212:215], v[68:71]
	ds_read_b128 v[178:181], v250 offset:36864
	v_mfma_f32_16x16x32_bf16 v[60:63], v[156:159], v[216:219], v[60:63]
	ds_read_b128 v[182:185], v250 offset:38912
	v_mfma_f32_16x16x32_bf16 v[52:55], v[156:159], v[220:223], v[52:55]
	v_mfma_f32_16x16x32_bf16 v[44:47], v[156:159], v[224:227], v[44:47]
	v_mfma_f32_16x16x32_bf16 v[36:39], v[160:163], v[212:215], v[36:39]
	v_mfma_f32_16x16x32_bf16 v[28:31], v[160:163], v[216:219], v[28:31]
	v_mfma_f32_16x16x32_bf16 v[20:23], v[160:163], v[220:223], v[20:23]
	v_mfma_f32_16x16x32_bf16 v[12:15], v[160:163], v[224:227], v[12:15]
	v_mfma_f32_16x16x32_bf16 v[8:11], v[164:167], v[212:215], v[8:11]
	v_mfma_f32_16x16x32_bf16 v[4:7], v[164:167], v[216:219], v[4:7]
	v_mfma_f32_16x16x32_bf16 v[0:3], v[164:167], v[220:223], v[0:3]
	v_mfma_f32_16x16x32_bf16 v[108:111], v[164:167], v[224:227], v[108:111]
	s_waitcnt lgkmcnt(0)
	v_mfma_f32_16x16x32_bf16 v[124:127], v[192:195], v[168:171], v[124:127]
	ds_read_b128 v[212:215], v250 offset:40960
	v_mfma_f32_16x16x32_bf16 v[120:123], v[192:195], v[172:175], v[120:123]
	ds_read_b128 v[216:219], v250 offset:43008
	v_mfma_f32_16x16x32_bf16 v[116:119], v[192:195], v[178:181], v[116:119]
	ds_read_b128 v[220:223], v250 offset:45056
	v_mfma_f32_16x16x32_bf16 v[112:115], v[192:195], v[182:185], v[112:115]
	ds_read_b128 v[224:227], v250 offset:47104
	v_mfma_f32_16x16x32_bf16 v[104:107], v[198:201], v[168:171], v[104:107]
	v_mfma_f32_16x16x32_bf16 v[96:99], v[198:201], v[172:175], v[96:99]
	v_mfma_f32_16x16x32_bf16 v[88:91], v[198:201], v[178:181], v[88:91]
	v_mfma_f32_16x16x32_bf16 v[80:83], v[198:201], v[182:185], v[80:83]
	v_mfma_f32_16x16x32_bf16 v[72:75], v[204:207], v[168:171], v[72:75]
	v_mfma_f32_16x16x32_bf16 v[64:67], v[204:207], v[172:175], v[64:67]
	v_mfma_f32_16x16x32_bf16 v[56:59], v[204:207], v[178:181], v[56:59]
	v_mfma_f32_16x16x32_bf16 v[48:51], v[204:207], v[182:185], v[48:51]
	v_mfma_f32_16x16x32_bf16 v[40:43], v[208:211], v[168:171], v[40:43]
	v_mfma_f32_16x16x32_bf16 v[32:35], v[208:211], v[172:175], v[32:35]
	v_mfma_f32_16x16x32_bf16 v[24:27], v[208:211], v[178:181], v[24:27]
	v_mfma_f32_16x16x32_bf16 v[16:19], v[208:211], v[182:185], v[16:19]
	s_waitcnt lgkmcnt(0)
	v_mfma_f32_16x16x32_bf16 v[100:103], v[192:195], v[212:215], v[100:103]
	v_mfma_f32_16x16x32_bf16 v[92:95], v[192:195], v[216:219], v[92:95]
	v_mfma_f32_16x16x32_bf16 v[84:87], v[192:195], v[220:223], v[84:87]
	v_mfma_f32_16x16x32_bf16 v[76:79], v[192:195], v[224:227], v[76:79]
	v_mfma_f32_16x16x32_bf16 v[68:71], v[198:201], v[212:215], v[68:71]
	v_mfma_f32_16x16x32_bf16 v[60:63], v[198:201], v[216:219], v[60:63]
	v_mfma_f32_16x16x32_bf16 v[52:55], v[198:201], v[220:223], v[52:55]
	v_mfma_f32_16x16x32_bf16 v[44:47], v[198:201], v[224:227], v[44:47]
	v_mfma_f32_16x16x32_bf16 v[36:39], v[204:207], v[212:215], v[36:39]
	v_mfma_f32_16x16x32_bf16 v[28:31], v[204:207], v[216:219], v[28:31]
	v_mfma_f32_16x16x32_bf16 v[20:23], v[204:207], v[220:223], v[20:23]
	v_mfma_f32_16x16x32_bf16 v[12:15], v[204:207], v[224:227], v[12:15]
	s_add_u32 s2, s2, 0x80
	s_addc_u32 s3, s3, 0
	s_cmpk_eq_i32 s2, 0x1580
	s_mov_b32 s10, s11
	v_mfma_f32_16x16x32_bf16 v[8:11], v[208:211], v[212:215], v[8:11]
	v_mfma_f32_16x16x32_bf16 v[4:7], v[208:211], v[216:219], v[4:7]
	v_mfma_f32_16x16x32_bf16 v[0:3], v[208:211], v[220:223], v[0:3]
	v_mfma_f32_16x16x32_bf16 v[108:111], v[208:211], v[224:227], v[108:111]
	s_cbranch_scc0 .LBB0_1143
	s_add_i32 s2, 0, 0x10000
	v_add_u32_e32 v136, s2, v149
	v_add_u32_e32 v137, v136, v147
	s_waitcnt vmcnt(0)
	s_barrier
	ds_read_b128 v[128:131], v137
	ds_read_b128 v[132:135], v137 offset:2048
	ds_read_b128 v[150:153], v137 offset:4096
	ds_read_b128 v[154:157], v137 offset:6144
	v_add_u32_e32 v137, s2, v148
	v_add_u32_e32 v147, v137, v147
	ds_read_b128 v[158:161], v147 offset:32768
	ds_read_b128 v[162:165], v147 offset:34816
	ds_read_b128 v[166:169], v147 offset:36864
	ds_read_b128 v[170:173], v147 offset:38912
	s_waitcnt lgkmcnt(0)
	v_mfma_f32_16x16x32_bf16 v[124:127], v[128:131], v[158:161], v[124:127]
	v_mfma_f32_16x16x32_bf16 v[120:123], v[128:131], v[162:165], v[120:123]
	v_mfma_f32_16x16x32_bf16 v[116:119], v[128:131], v[166:169], v[116:119]
	v_mfma_f32_16x16x32_bf16 v[112:115], v[128:131], v[170:173], v[112:115]
	v_mfma_f32_16x16x32_bf16 v[104:107], v[132:135], v[158:161], v[104:107]
	v_mfma_f32_16x16x32_bf16 v[72:75], v[150:153], v[158:161], v[72:75]
	v_mfma_f32_16x16x32_bf16 v[64:67], v[150:153], v[162:165], v[64:67]
	v_mfma_f32_16x16x32_bf16 v[56:59], v[150:153], v[166:169], v[56:59]
	v_mfma_f32_16x16x32_bf16 v[48:51], v[150:153], v[170:173], v[48:51]
	v_mfma_f32_16x16x32_bf16 v[178:181], v[132:135], v[162:165], v[96:99]
	v_mfma_f32_16x16x32_bf16 v[182:185], v[132:135], v[166:169], v[88:91]
	v_mfma_f32_16x16x32_bf16 v[186:189], v[132:135], v[170:173], v[80:83]
	v_mfma_f32_16x16x32_bf16 v[158:161], v[154:157], v[158:161], v[40:43]
	v_mfma_f32_16x16x32_bf16 v[162:165], v[154:157], v[162:165], v[32:35]
	v_mfma_f32_16x16x32_bf16 v[166:169], v[154:157], v[166:169], v[24:27]
	v_mfma_f32_16x16x32_bf16 v[170:173], v[154:157], v[170:173], v[16:19]
	s_nop 2
	ds_read_b128 v[16:19], v147 offset:40960
	ds_read_b128 v[24:27], v147 offset:43008
	ds_read_b128 v[32:35], v147 offset:45056
	ds_read_b128 v[40:43], v147 offset:47104
	s_waitcnt lgkmcnt(0)
	v_mfma_f32_16x16x32_bf16 v[100:103], v[128:131], v[16:19], v[100:103]
	v_mfma_f32_16x16x32_bf16 v[92:95], v[128:131], v[24:27], v[92:95]
	v_mfma_f32_16x16x32_bf16 v[192:195], v[128:131], v[32:35], v[84:87]
	v_mfma_f32_16x16x32_bf16 v[76:79], v[128:131], v[40:43], v[76:79]
	v_mfma_f32_16x16x32_bf16 v[68:71], v[132:135], v[16:19], v[68:71]
	v_mfma_f32_16x16x32_bf16 v[60:63], v[132:135], v[24:27], v[60:63]
	v_mfma_f32_16x16x32_bf16 v[128:131], v[132:135], v[32:35], v[52:55]
	v_mfma_f32_16x16x32_bf16 v[44:47], v[132:135], v[40:43], v[44:47]
	v_mfma_f32_16x16x32_bf16 v[132:135], v[150:153], v[16:19], v[36:39]
	v_mfma_f32_16x16x32_bf16 v[198:201], v[150:153], v[24:27], v[28:31]
	v_mfma_f32_16x16x32_bf16 v[204:207], v[150:153], v[32:35], v[20:23]
	v_mfma_f32_16x16x32_bf16 v[148:151], v[150:153], v[40:43], v[12:15]
	v_mfma_f32_16x16x32_bf16 v[208:211], v[154:157], v[16:19], v[8:11]
	v_mfma_f32_16x16x32_bf16 v[212:215], v[154:157], v[24:27], v[4:7]
	v_mfma_f32_16x16x32_bf16 v[216:219], v[154:157], v[32:35], v[0:3]
	v_mfma_f32_16x16x32_bf16 v[154:157], v[154:157], v[40:43], v[108:111]
	s_nop 1
	v_add_u32_e32 v0, v136, v146
	v_add_u32_e32 v136, v137, v146
	ds_read_b128 v[108:111], v0
	ds_read_b128 v[220:223], v0 offset:2048
	ds_read_b128 v[224:227], v0 offset:4096
	ds_read_b128 v[228:231], v0 offset:6144
	ds_read_b128 v[0:3], v136 offset:32768
	ds_read_b128 v[4:7], v136 offset:34816
	ds_read_b128 v[232:235], v136 offset:36864
	ds_read_b128 v[236:239], v136 offset:38912
	s_waitcnt lgkmcnt(0)
	v_mfma_f32_16x16x32_bf16 v[88:91], v[108:111], v[0:3], v[124:127]
	v_mfma_f32_16x16x32_bf16 v[96:99], v[108:111], v[4:7], v[120:123]
	v_mfma_f32_16x16x32_bf16 v[80:83], v[108:111], v[232:235], v[116:119]
	v_mfma_f32_16x16x32_bf16 v[84:87], v[108:111], v[236:239], v[112:115]
	v_mfma_f32_16x16x32_bf16 v[40:43], v[220:223], v[0:3], v[104:107]
	v_mfma_f32_16x16x32_bf16 v[52:55], v[220:223], v[4:7], v[178:181]
	v_mfma_f32_16x16x32_bf16 v[32:35], v[220:223], v[232:235], v[182:185]
	v_mfma_f32_16x16x32_bf16 v[36:39], v[220:223], v[236:239], v[186:189]
	v_mfma_f32_16x16x32_bf16 v[24:27], v[224:227], v[0:3], v[72:75]
	v_mfma_f32_16x16x32_bf16 v[28:31], v[224:227], v[4:7], v[64:67]
	v_mfma_f32_16x16x32_bf16 v[16:19], v[224:227], v[232:235], v[56:59]
	v_mfma_f32_16x16x32_bf16 v[20:23], v[224:227], v[236:239], v[48:51]
	v_mfma_f32_16x16x32_bf16 v[8:11], v[228:231], v[0:3], v[158:161]
	v_mfma_f32_16x16x32_bf16 v[12:15], v[228:231], v[4:7], v[162:165]
	v_mfma_f32_16x16x32_bf16 v[0:3], v[228:231], v[232:235], v[166:169]
	v_mfma_f32_16x16x32_bf16 v[4:7], v[228:231], v[236:239], v[170:173]
	ds_read_b128 v[48:51], v136 offset:40960
	ds_read_b128 v[64:67], v136 offset:43008
	ds_read_b128 v[158:161], v136 offset:45056
	ds_read_b128 v[162:165], v136 offset:47104
	s_waitcnt lgkmcnt(0)
	v_mfma_f32_16x16x32_bf16 v[104:107], v[220:223], v[48:51], v[68:71]
	v_cmp_ne_u32_e32 vcc, 0, v138
	v_cmp_eq_u32_e64 s[2:3], 0, v138
	s_waitcnt vmcnt(0)
	v_lshl_or_b32 v68, v140, 2, v141
	v_lshl_add_u32 v69, v139, 2, 0
	v_mfma_f32_16x16x32_bf16 v[120:123], v[108:111], v[48:51], v[100:103]
	v_lshl_add_u32 v152, v68, 9, v69
	v_add_u32_e32 v153, 0x400, v152
	v_add_u32_e32 v147, 0x6000, v152
	v_mfma_f32_16x16x32_bf16 v[124:127], v[108:111], v[64:67], v[92:95]
	v_add_u32_e32 v146, 0x6400, v152
	s_barrier
	v_mfma_f32_16x16x32_bf16 v[112:115], v[108:111], v[158:161], v[192:195]
	v_mfma_f32_16x16x32_bf16 v[116:119], v[108:111], v[162:165], v[76:79]
	v_mfma_f32_16x16x32_bf16 v[108:111], v[220:223], v[64:67], v[60:63]
	v_mfma_f32_16x16x32_bf16 v[92:95], v[220:223], v[158:161], v[128:131]
	v_mfma_f32_16x16x32_bf16 v[100:103], v[220:223], v[162:165], v[44:47]
	v_mfma_f32_16x16x32_bf16 v[56:59], v[224:227], v[48:51], v[132:135]
	v_mfma_f32_16x16x32_bf16 v[60:63], v[224:227], v[64:67], v[198:201]
	v_mfma_f32_16x16x32_bf16 v[44:47], v[224:227], v[158:161], v[204:207]
	v_mfma_f32_16x16x32_bf16 v[72:75], v[224:227], v[162:165], v[148:151]
	v_mfma_f32_16x16x32_bf16 v[48:51], v[228:231], v[48:51], v[208:211]
	s_nop 1
	v_add_u32_e32 v151, 0x2000, v152
	v_add_u32_e32 v150, 0x2400, v152
	v_add_u32_e32 v149, 0x4000, v152
	v_mfma_f32_16x16x32_bf16 v[64:67], v[228:231], v[64:67], v[212:215]
	v_add_u32_e32 v148, 0x4400, v152
	v_mfma_f32_16x16x32_bf16 v[68:71], v[228:231], v[158:161], v[216:219]
	v_mfma_f32_16x16x32_bf16 v[76:79], v[228:231], v[162:165], v[154:157]
	s_and_saveexec_b64 s[10:11], s[2:3]
	s_cbranch_execz .LBB0_1146
	ds_write2_b32 v152, v88, v96 offset1:16
	ds_write2_b32 v152, v89, v97 offset0:128 offset1:144
	ds_write2_b32 v153, v90, v98 offset1:16
	ds_write2_b32 v153, v91, v99 offset0:128 offset1:144
	ds_write2_b32 v152, v80, v84 offset0:32 offset1:48
	ds_write2_b32 v152, v81, v85 offset0:160 offset1:176
	ds_write2_b32 v153, v82, v86 offset0:32 offset1:48
	ds_write2_b32 v153, v83, v87 offset0:160 offset1:176
	ds_write2_b32 v152, v120, v124 offset0:64 offset1:80
	ds_write2_b32 v152, v121, v125 offset0:192 offset1:208
	ds_write2_b32 v153, v122, v126 offset0:64 offset1:80
	ds_write2_b32 v153, v123, v127 offset0:192 offset1:208
	ds_write2_b32 v152, v112, v116 offset0:96 offset1:112
	ds_write2_b32 v152, v113, v117 offset0:224 offset1:240
	ds_write2_b32 v153, v114, v118 offset0:96 offset1:112
	ds_write2_b32 v153, v115, v119 offset0:224 offset1:240
	ds_write2_b32 v151, v40, v52 offset1:16
	ds_write2_b32 v151, v41, v53 offset0:128 offset1:144
	ds_write2_b32 v150, v42, v54 offset1:16
	ds_write2_b32 v150, v43, v55 offset0:128 offset1:144
	ds_write2_b32 v151, v32, v36 offset0:32 offset1:48
	ds_write2_b32 v151, v33, v37 offset0:160 offset1:176
	ds_write2_b32 v150, v34, v38 offset0:32 offset1:48
	ds_write2_b32 v150, v35, v39 offset0:160 offset1:176
	ds_write2_b32 v151, v104, v108 offset0:64 offset1:80
	ds_write2_b32 v151, v105, v109 offset0:192 offset1:208
	ds_write2_b32 v150, v106, v110 offset0:64 offset1:80
	ds_write2_b32 v150, v107, v111 offset0:192 offset1:208
	ds_write2_b32 v151, v92, v100 offset0:96 offset1:112
	ds_write2_b32 v151, v93, v101 offset0:224 offset1:240
	ds_write2_b32 v150, v94, v102 offset0:96 offset1:112
	ds_write2_b32 v150, v95, v103 offset0:224 offset1:240
	ds_write2_b32 v149, v24, v28 offset1:16
	ds_write2_b32 v149, v25, v29 offset0:128 offset1:144
	ds_write2_b32 v148, v26, v30 offset1:16
	ds_write2_b32 v148, v27, v31 offset0:128 offset1:144
	ds_write2_b32 v149, v16, v20 offset0:32 offset1:48
	ds_write2_b32 v149, v17, v21 offset0:160 offset1:176
	ds_write2_b32 v148, v18, v22 offset0:32 offset1:48
	ds_write2_b32 v148, v19, v23 offset0:160 offset1:176
	ds_write2_b32 v149, v56, v60 offset0:64 offset1:80
	ds_write2_b32 v149, v57, v61 offset0:192 offset1:208
	ds_write2_b32 v148, v58, v62 offset0:64 offset1:80
	ds_write2_b32 v148, v59, v63 offset0:192 offset1:208
	ds_write2_b32 v149, v44, v72 offset0:96 offset1:112
	ds_write2_b32 v149, v45, v73 offset0:224 offset1:240
	ds_write2_b32 v148, v46, v74 offset0:96 offset1:112
	ds_write2_b32 v148, v47, v75 offset0:224 offset1:240
	ds_write2_b32 v147, v8, v12 offset1:16
	ds_write2_b32 v147, v9, v13 offset0:128 offset1:144
	ds_write2_b32 v146, v10, v14 offset1:16
	ds_write2_b32 v146, v11, v15 offset0:128 offset1:144
	ds_write2_b32 v147, v0, v4 offset0:32 offset1:48
	ds_write2_b32 v147, v1, v5 offset0:160 offset1:176
	ds_write2_b32 v146, v2, v6 offset0:32 offset1:48
	ds_write2_b32 v146, v3, v7 offset0:160 offset1:176
	ds_write2_b32 v147, v48, v64 offset0:64 offset1:80
	ds_write2_b32 v147, v49, v65 offset0:192 offset1:208
	ds_write2_b32 v146, v50, v66 offset0:64 offset1:80
	ds_write2_b32 v146, v51, v67 offset0:192 offset1:208
	ds_write2_b32 v147, v68, v76 offset0:96 offset1:112
	ds_write2_b32 v147, v69, v77 offset0:224 offset1:240
	ds_write2_b32 v146, v70, v78 offset0:96 offset1:112
	ds_write2_b32 v146, v71, v79 offset0:224 offset1:240
